# K-loop LDS-DMA: saddr form + A-operand loads issued first in each phase
# speedup vs baseline: 1.0066x; 1.0041x over previous
; #define PG8_STAGE(bufoff, gbase, voff) do { _Pragma("unroll") for (int _i = 0; _i < 2; ++_i) \
;         __builtin_amdgcn_global_load_lds((const unsigned*)((const char*)(gbase) + (voff)[_i]), (LAS unsigned*)(lds + (bufoff) + ldsw + _i * 8192), 16, 0, 0); } while (0)
; #define PG8_LDA(dst, b, h) do { _Pragma("unroll") for (int m = 0; m < 4; ++m) _Pragma("unroll") for (int k = 0; k < 2; ++k) dst[m][k] = *(const LAS bf16x8*)(lds + PG8_SA(b, h) + aoff + m * 2048 + k * 1024); } while (0)
; #define PG8_LDB(dst, b, h) do { _Pragma("unroll") for (int n = 0; n < 2; ++n) _Pragma("unroll") for (int k = 0; k < 2; ++k) dst[n][k] = *(const LAS bf16x8*)(lds + PG8_SB(b, h) + boff + n * 2048 + k * 1024); } while (0)
; #define PG8_MMA(ai, bj, At, Bt) do { __builtin_amdgcn_s_setprio(1); _Pragma("unroll") for (int m = 0; m < 4; ++m) _Pragma("unroll") for (int n = 0; n < 2; ++n) _Pragma("unroll") for (int k = 0; k < 2; ++k) \
;         acc[ai][bj][m][n] = __builtin_amdgcn_mfma_f32_16x16x32_bf16(Bt[n][k], At[m][k], acc[ai][bj][m][n], 0, 0, 0); __builtin_amdgcn_s_setprio(0); } while (0)
; #define PG8_WAIT_V(n) asm volatile("s_waitcnt vmcnt(" #n ")" ::: "memory")
; #define PG8_WAIT_L(n) asm volatile("s_waitcnt lgkmcnt(" #n ")" ::: "memory")
; #define PG8_BAR __builtin_amdgcn_s_barrier()
; #define PG8_SCHED __builtin_amdgcn_sched_barrier(0)
; template <class Epi, class Sched, bool ALIGN_EPI>
; __device__ __forceinline__ void gemm_phase(LAS unsigned char* lds, const Gemm g, const Sched& S, const Epi& E) {
;     ...
;             const char* a1 = cA + (size_t)(t + 1) * kstep;
;             const char* a2 = last ? nA : cA + (size_t)(t + 2) * kstep; const char* b2 = last ? nB : cB + (size_t)(t + 2) * kstep;
;             const char* a3 = a2 + kstep; const char* b3 = b2 + kstep;
;             PG8_LDB(B0, 0, 0); PG8_LDB(B1, 0, 1); PG8_SCHED; PG8_LDA(At, 0, 0); PG8_STAGE(PG8_SA(1, 1), a1 + hstepA, voffA);
;             PG8_WAIT_V(8); PG8_WAIT_L(0); PG8_BAR; PG8_MMA(0, 0, At, B0); PG8_MMA(0, 1, At, B1); PG8_BAR; PG8_SCHED;
;             PG8_LDA(At, 0, 1); PG8_STAGE(PG8_SB(0, 0), b2, voffB); PG8_STAGE(PG8_SB(0, 1), b2 + hstepB, voffB); PG8_STAGE(PG8_SA(0, 0), a2, voffA);
;             PG8_WAIT_V(8); PG8_WAIT_L(0); PG8_BAR; PG8_MMA(1, 0, At, B0); PG8_MMA(1, 1, At, B1); PG8_BAR; PG8_SCHED;
.LBB0_209:
	s_add_u32 s46, s44, 0xfff00080
	s_addc_u32 s47, s45, -1
	s_add_i32 s52, 0, 0x10000
	s_cmp_eq_u32 s92, 60
	s_cselect_b32 s55, s56, s47
	s_cselect_b32 s54, s57, s46
	s_cselect_b32 s47, s63, s81
	s_cselect_b32 s46, s64, s65
	s_add_i32 s53, 0, 0x14000
	v_add_u32_e32 v140, s52, v247
	v_add_u32_e32 v156, s53, v247
	s_add_i32 m0, s49, 0xc000
	s_nop 0
	global_load_lds_dwordx4 v220, s[44:45]
	s_add_i32 m0, s49, 0xe000
	s_nop 0
	global_load_lds_dwordx4 v222, s[44:45]
	ds_read_b128 v[104:107], v140
	ds_read_b128 v[112:115], v140 offset:1024
	ds_read_b128 v[136:139], v140 offset:2048
	ds_read_b128 v[140:143], v140 offset:3072
	ds_read_b128 v[144:147], v156
	ds_read_b128 v[148:151], v156 offset:1024
	ds_read_b128 v[152:155], v156 offset:2048
	ds_read_b128 v[156:159], v156 offset:3072
	ds_read_b128 v[160:163], v248
	ds_read_b128 v[164:167], v248 offset:1024
	ds_read_b128 v[168:171], v248 offset:2048
	ds_read_b128 v[172:175], v248 offset:3072
	ds_read_b128 v[176:179], v248 offset:4096
	ds_read_b128 v[180:183], v248 offset:5120
	ds_read_b128 v[184:187], v248 offset:6144
	ds_read_b128 v[188:191], v248 offset:7168
	s_waitcnt vmcnt(8)
	s_waitcnt lgkmcnt(0)
	s_barrier
	s_setprio 1
	s_waitcnt lgkmcnt(0)
	v_mfma_f32_16x16x32_bf16 v[132:135], v[104:107], v[160:163], v[132:135]
	v_mfma_f32_16x16x32_bf16 v[128:131], v[136:139], v[160:163], v[128:131]
	v_mfma_f32_16x16x32_bf16 v[116:119], v[104:107], v[168:171], v[116:119]
	v_mfma_f32_16x16x32_bf16 v[108:111], v[136:139], v[168:171], v[108:111]
	v_mfma_f32_16x16x32_bf16 v[96:99], v[104:107], v[176:179], v[96:99]
	v_mfma_f32_16x16x32_bf16 v[88:91], v[136:139], v[176:179], v[88:91]
	v_mfma_f32_16x16x32_bf16 v[80:83], v[104:107], v[184:187], v[80:83]
	v_mfma_f32_16x16x32_bf16 v[72:75], v[136:139], v[184:187], v[72:75]
	v_mfma_f32_16x16x32_bf16 v[132:135], v[112:115], v[164:167], v[132:135]
	v_mfma_f32_16x16x32_bf16 v[128:131], v[140:143], v[164:167], v[128:131]
	v_mfma_f32_16x16x32_bf16 v[116:119], v[112:115], v[172:175], v[116:119]
	v_mfma_f32_16x16x32_bf16 v[108:111], v[140:143], v[172:175], v[108:111]
	v_mfma_f32_16x16x32_bf16 v[96:99], v[112:115], v[180:183], v[96:99]
	v_mfma_f32_16x16x32_bf16 v[88:91], v[140:143], v[180:183], v[88:91]
	v_mfma_f32_16x16x32_bf16 v[80:83], v[112:115], v[188:191], v[80:83]
	v_mfma_f32_16x16x32_bf16 v[72:75], v[140:143], v[188:191], v[72:75]
	s_setprio 0
	s_setprio 1
	v_mfma_f32_16x16x32_bf16 v[124:127], v[144:147], v[160:163], v[124:127]
	v_mfma_f32_16x16x32_bf16 v[120:123], v[152:155], v[160:163], v[120:123]
	v_mfma_f32_16x16x32_bf16 v[100:103], v[144:147], v[168:171], v[100:103]
	v_mfma_f32_16x16x32_bf16 v[92:95], v[152:155], v[168:171], v[92:95]
	v_mfma_f32_16x16x32_bf16 v[84:87], v[144:147], v[176:179], v[84:87]
	v_mfma_f32_16x16x32_bf16 v[76:79], v[152:155], v[176:179], v[76:79]
	v_mfma_f32_16x16x32_bf16 v[68:71], v[144:147], v[184:187], v[68:71]
	v_mfma_f32_16x16x32_bf16 v[64:67], v[152:155], v[184:187], v[64:67]
	v_mfma_f32_16x16x32_bf16 v[124:127], v[148:151], v[164:167], v[124:127]
	v_mfma_f32_16x16x32_bf16 v[120:123], v[156:159], v[164:167], v[120:123]
	v_mfma_f32_16x16x32_bf16 v[100:103], v[148:151], v[172:175], v[100:103]
	v_mfma_f32_16x16x32_bf16 v[92:95], v[156:159], v[172:175], v[92:95]
	v_mfma_f32_16x16x32_bf16 v[84:87], v[148:151], v[180:183], v[84:87]
	v_mfma_f32_16x16x32_bf16 v[76:79], v[156:159], v[180:183], v[76:79]
	v_mfma_f32_16x16x32_bf16 v[68:71], v[148:151], v[188:191], v[68:71]
	v_mfma_f32_16x16x32_bf16 v[64:67], v[156:159], v[188:191], v[64:67]
	s_setprio 0
	s_barrier
	s_add_i32 s52, s52, s50
	s_mov_b32 m0, s49
	s_nop 0
	global_load_lds_dwordx4 v218, s[54:55]
	s_mov_b32 m0, s67
	s_nop 0
	global_load_lds_dwordx4 v214, s[54:55]
	s_mov_b32 m0, s52
	ds_read_b128 v[160:163], v248 offset:16384
	ds_read_b128 v[164:167], v248 offset:17408
	ds_read_b128 v[168:171], v248 offset:18432
	ds_read_b128 v[172:175], v248 offset:19456
	ds_read_b128 v[176:179], v248 offset:20480
	ds_read_b128 v[180:183], v248 offset:21504
	ds_read_b128 v[184:187], v248 offset:22528
	ds_read_b128 v[188:191], v248 offset:23552
	global_load_lds_dwordx4 v216, s[46:47]
	s_add_i32 m0, s52, 0x2000
	s_add_u32 vcc_lo, s46, 0x100000
	s_addc_u32 vcc_hi, s47, 0
	s_add_i32 s52, s53, s50
	global_load_lds_dwordx4 v212, s[46:47]
	s_mov_b32 m0, s52
	s_nop 0
	global_load_lds_dwordx4 v216, vcc
	s_add_i32 m0, s52, 0x2000
	s_nop 0
	global_load_lds_dwordx4 v212, vcc
	s_waitcnt vmcnt(8)
	s_waitcnt lgkmcnt(0)
	s_barrier
	s_setprio 1
	s_waitcnt lgkmcnt(0)
	v_mfma_f32_16x16x32_bf16 v[60:63], v[104:107], v[160:163], v[60:63]
	v_mfma_f32_16x16x32_bf16 v[56:59], v[136:139], v[160:163], v[56:59]
	v_mfma_f32_16x16x32_bf16 v[44:47], v[104:107], v[168:171], v[44:47]
	v_mfma_f32_16x16x32_bf16 v[40:43], v[136:139], v[168:171], v[40:43]
	v_mfma_f32_16x16x32_bf16 v[32:35], v[104:107], v[176:179], v[32:35]
	v_mfma_f32_16x16x32_bf16 v[24:27], v[136:139], v[176:179], v[24:27]
	v_mfma_f32_16x16x32_bf16 v[16:19], v[104:107], v[184:187], v[16:19]
	v_mfma_f32_16x16x32_bf16 v[8:11], v[136:139], v[184:187], v[8:11]
	v_mfma_f32_16x16x32_bf16 v[60:63], v[112:115], v[164:167], v[60:63]
	v_mfma_f32_16x16x32_bf16 v[56:59], v[140:143], v[164:167], v[56:59]
	v_mfma_f32_16x16x32_bf16 v[44:47], v[112:115], v[172:175], v[44:47]
	v_mfma_f32_16x16x32_bf16 v[40:43], v[140:143], v[172:175], v[40:43]
	v_mfma_f32_16x16x32_bf16 v[32:35], v[112:115], v[180:183], v[32:35]
	v_mfma_f32_16x16x32_bf16 v[24:27], v[140:143], v[180:183], v[24:27]
	v_mfma_f32_16x16x32_bf16 v[16:19], v[112:115], v[188:191], v[16:19]
	v_mfma_f32_16x16x32_bf16 v[8:11], v[140:143], v[188:191], v[8:11]
	s_setprio 0
	s_setprio 1
	v_mfma_f32_16x16x32_bf16 v[52:55], v[144:147], v[160:163], v[52:55]
	v_mfma_f32_16x16x32_bf16 v[48:51], v[152:155], v[160:163], v[48:51]
	v_mfma_f32_16x16x32_bf16 v[36:39], v[144:147], v[168:171], v[36:39]
	v_mfma_f32_16x16x32_bf16 v[28:31], v[152:155], v[168:171], v[28:31]
	v_mfma_f32_16x16x32_bf16 v[20:23], v[144:147], v[176:179], v[20:23]
	v_mfma_f32_16x16x32_bf16 v[12:15], v[152:155], v[176:179], v[12:15]
	v_mfma_f32_16x16x32_bf16 v[4:7], v[144:147], v[184:187], v[4:7]
	v_mfma_f32_16x16x32_bf16 v[0:3], v[152:155], v[184:187], v[0:3]
	v_mfma_f32_16x16x32_bf16 v[52:55], v[148:151], v[164:167], v[52:55]
	v_mfma_f32_16x16x32_bf16 v[48:51], v[156:159], v[164:167], v[48:51]
	v_mfma_f32_16x16x32_bf16 v[36:39], v[148:151], v[172:175], v[36:39]
	v_mfma_f32_16x16x32_bf16 v[28:31], v[156:159], v[172:175], v[28:31]
	v_mfma_f32_16x16x32_bf16 v[20:23], v[148:151], v[180:183], v[20:23]
	v_mfma_f32_16x16x32_bf16 v[12:15], v[156:159], v[180:183], v[12:15]
	v_mfma_f32_16x16x32_bf16 v[4:7], v[148:151], v[188:191], v[4:7]
	v_mfma_f32_16x16x32_bf16 v[0:3], v[156:159], v[188:191], v[0:3]
	s_setprio 0
	s_barrier
; #define PG8_STAGE(bufoff, gbase, voff) do { _Pragma("unroll") for (int _i = 0; _i < 2; ++_i) \
;         __builtin_amdgcn_global_load_lds((const unsigned*)((const char*)(gbase) + (voff)[_i]), (LAS unsigned*)(lds + (bufoff) + ldsw + _i * 8192), 16, 0, 0); } while (0)
; #define PG8_LDA(dst, b, h) do { _Pragma("unroll") for (int m = 0; m < 4; ++m) _Pragma("unroll") for (int k = 0; k < 2; ++k) dst[m][k] = *(const LAS bf16x8*)(lds + PG8_SA(b, h) + aoff + m * 2048 + k * 1024); } while (0)
; #define PG8_LDB(dst, b, h) do { _Pragma("unroll") for (int n = 0; n < 2; ++n) _Pragma("unroll") for (int k = 0; k < 2; ++k) dst[n][k] = *(const LAS bf16x8*)(lds + PG8_SB(b, h) + boff + n * 2048 + k * 1024); } while (0)
; #define PG8_MMA(ai, bj, At, Bt) do { __builtin_amdgcn_s_setprio(1); _Pragma("unroll") for (int m = 0; m < 4; ++m) _Pragma("unroll") for (int n = 0; n < 2; ++n) _Pragma("unroll") for (int k = 0; k < 2; ++k) \
;         acc[ai][bj][m][n] = __builtin_amdgcn_mfma_f32_16x16x32_bf16(Bt[n][k], At[m][k], acc[ai][bj][m][n], 0, 0, 0); __builtin_amdgcn_s_setprio(0); } while (0)
; #define PG8_WAIT_V(n) asm volatile("s_waitcnt vmcnt(" #n ")" ::: "memory")
; #define PG8_WAIT_L(n) asm volatile("s_waitcnt lgkmcnt(" #n ")" ::: "memory")
; #define PG8_BAR __builtin_amdgcn_s_barrier()
; #define PG8_SCHED __builtin_amdgcn_sched_barrier(0)
; template <class Epi, class Sched, bool ALIGN_EPI>
; __device__ __forceinline__ void gemm_phase(LAS unsigned char* lds, const Gemm g, const Sched& S, const Epi& E) {
;     ...
;             PG8_LDB(B0, 1, 0); PG8_LDB(B1, 1, 1); PG8_SCHED; PG8_LDA(At, 1, 0); PG8_STAGE(PG8_SA(0, 1), a2 + hstepA, voffA);
;             PG8_WAIT_V(8); PG8_WAIT_L(0); PG8_BAR; PG8_MMA(0, 0, At, B0); PG8_MMA(0, 1, At, B1); PG8_BAR; PG8_SCHED;
;             PG8_LDA(At, 1, 1); PG8_STAGE(PG8_SB(1, 0), b3, voffB); PG8_STAGE(PG8_SB(1, 1), b3 + hstepB, voffB); PG8_STAGE(PG8_SA(1, 0), a3, voffA);
;             PG8_WAIT_V(8); PG8_WAIT_L(0); PG8_BAR; PG8_MMA(1, 0, At, B0); PG8_MMA(1, 1, At, B1); PG8_BAR; PG8_SCHED;
;         }
	s_add_i32 s52, 0, 0x18000
	s_add_i32 s53, 0, 0x1c000
	v_add_u32_e32 v140, s52, v247
	v_add_u32_e32 v156, s53, v247
	s_add_u32 s54, s54, 0x100000
	s_addc_u32 s55, s55, 0
	s_mov_b32 m0, s86
	s_nop 0
	global_load_lds_dwordx4 v218, s[54:55]
	s_mov_b32 m0, s66
	s_nop 0
	global_load_lds_dwordx4 v214, s[54:55]
	ds_read_b128 v[104:107], v140
	ds_read_b128 v[112:115], v140 offset:1024
	ds_read_b128 v[136:139], v140 offset:2048
	ds_read_b128 v[140:143], v140 offset:3072
	ds_read_b128 v[144:147], v156
	ds_read_b128 v[148:151], v156 offset:1024
	ds_read_b128 v[152:155], v156 offset:2048
	ds_read_b128 v[156:159], v156 offset:3072
	ds_read_b128 v[160:163], v248 offset:32768
	ds_read_b128 v[164:167], v248 offset:33792
	ds_read_b128 v[168:171], v248 offset:34816
	ds_read_b128 v[172:175], v248 offset:35840
	ds_read_b128 v[176:179], v248 offset:36864
	ds_read_b128 v[180:183], v248 offset:37888
	ds_read_b128 v[184:187], v248 offset:38912
	ds_read_b128 v[188:191], v248 offset:39936
	s_waitcnt vmcnt(8)
	s_waitcnt lgkmcnt(0)
	s_barrier
	s_setprio 1
	s_waitcnt lgkmcnt(0)
	v_mfma_f32_16x16x32_bf16 v[132:135], v[104:107], v[160:163], v[132:135]
	v_mfma_f32_16x16x32_bf16 v[128:131], v[136:139], v[160:163], v[128:131]
	v_mfma_f32_16x16x32_bf16 v[116:119], v[104:107], v[168:171], v[116:119]
	v_mfma_f32_16x16x32_bf16 v[108:111], v[136:139], v[168:171], v[108:111]
	v_mfma_f32_16x16x32_bf16 v[96:99], v[104:107], v[176:179], v[96:99]
	v_mfma_f32_16x16x32_bf16 v[88:91], v[136:139], v[176:179], v[88:91]
	v_mfma_f32_16x16x32_bf16 v[80:83], v[104:107], v[184:187], v[80:83]
	v_mfma_f32_16x16x32_bf16 v[72:75], v[136:139], v[184:187], v[72:75]
	v_mfma_f32_16x16x32_bf16 v[132:135], v[112:115], v[164:167], v[132:135]
	v_mfma_f32_16x16x32_bf16 v[128:131], v[140:143], v[164:167], v[128:131]
	v_mfma_f32_16x16x32_bf16 v[116:119], v[112:115], v[172:175], v[116:119]
	v_mfma_f32_16x16x32_bf16 v[108:111], v[140:143], v[172:175], v[108:111]
	v_mfma_f32_16x16x32_bf16 v[96:99], v[112:115], v[180:183], v[96:99]
	v_mfma_f32_16x16x32_bf16 v[88:91], v[140:143], v[180:183], v[88:91]
	v_mfma_f32_16x16x32_bf16 v[80:83], v[112:115], v[188:191], v[80:83]
	v_mfma_f32_16x16x32_bf16 v[72:75], v[140:143], v[188:191], v[72:75]
	s_setprio 0
	s_setprio 1
	v_mfma_f32_16x16x32_bf16 v[124:127], v[144:147], v[160:163], v[124:127]
	v_mfma_f32_16x16x32_bf16 v[120:123], v[152:155], v[160:163], v[120:123]
	v_mfma_f32_16x16x32_bf16 v[100:103], v[144:147], v[168:171], v[100:103]
	v_mfma_f32_16x16x32_bf16 v[92:95], v[152:155], v[168:171], v[92:95]
	v_mfma_f32_16x16x32_bf16 v[84:87], v[144:147], v[176:179], v[84:87]
	v_mfma_f32_16x16x32_bf16 v[76:79], v[152:155], v[176:179], v[76:79]
	v_mfma_f32_16x16x32_bf16 v[68:71], v[144:147], v[184:187], v[68:71]
	v_mfma_f32_16x16x32_bf16 v[64:67], v[152:155], v[184:187], v[64:67]
	v_mfma_f32_16x16x32_bf16 v[124:127], v[148:151], v[164:167], v[124:127]
	v_mfma_f32_16x16x32_bf16 v[120:123], v[156:159], v[164:167], v[120:123]
	v_mfma_f32_16x16x32_bf16 v[100:103], v[148:151], v[172:175], v[100:103]
	v_mfma_f32_16x16x32_bf16 v[92:95], v[156:159], v[172:175], v[92:95]
	v_mfma_f32_16x16x32_bf16 v[84:87], v[148:151], v[180:183], v[84:87]
	v_mfma_f32_16x16x32_bf16 v[76:79], v[156:159], v[180:183], v[76:79]
	v_mfma_f32_16x16x32_bf16 v[68:71], v[148:151], v[188:191], v[68:71]
	v_mfma_f32_16x16x32_bf16 v[64:67], v[156:159], v[188:191], v[64:67]
	s_setprio 0
	s_barrier
	s_add_i32 s52, s52, s50
	s_mov_b32 m0, s59
	s_add_u32 s100, s54, 0xfff00080
	s_addc_u32 s101, s55, -1
	global_load_lds_dwordx4 v218, s[100:101]
	s_mov_b32 m0, s4
	s_nop 0
	global_load_lds_dwordx4 v214, s[100:101]
	s_mov_b32 m0, s52
	ds_read_b128 v[160:163], v248 offset:49152
	ds_read_b128 v[164:167], v248 offset:50176
	ds_read_b128 v[168:171], v248 offset:51200
	ds_read_b128 v[172:175], v248 offset:52224
	ds_read_b128 v[176:179], v248 offset:53248
	ds_read_b128 v[180:183], v248 offset:54272
	ds_read_b128 v[184:187], v248 offset:55296
	ds_read_b128 v[188:191], v248 offset:56320
	s_add_u32 s100, s46, 0x80
	s_addc_u32 s101, s47, 0
	global_load_lds_dwordx4 v216, s[100:101]
	s_add_i32 m0, s52, 0x2000
	s_add_u32 s46, s46, 0x100080
	s_addc_u32 s47, s47, 0
	s_add_i32 s52, s53, s50
	global_load_lds_dwordx4 v212, s[100:101]
	s_mov_b32 m0, s52
	s_nop 0
	global_load_lds_dwordx4 v216, s[46:47]
	s_add_i32 m0, s52, 0x2000
	s_nop 0
	global_load_lds_dwordx4 v212, s[46:47]
	s_waitcnt vmcnt(8)
	s_waitcnt lgkmcnt(0)
	s_barrier
	s_setprio 1
	s_waitcnt lgkmcnt(0)
	v_mfma_f32_16x16x32_bf16 v[60:63], v[104:107], v[160:163], v[60:63]
	v_mfma_f32_16x16x32_bf16 v[56:59], v[136:139], v[160:163], v[56:59]
	v_mfma_f32_16x16x32_bf16 v[44:47], v[104:107], v[168:171], v[44:47]
	v_mfma_f32_16x16x32_bf16 v[40:43], v[136:139], v[168:171], v[40:43]
	v_mfma_f32_16x16x32_bf16 v[32:35], v[104:107], v[176:179], v[32:35]
	v_mfma_f32_16x16x32_bf16 v[24:27], v[136:139], v[176:179], v[24:27]
	v_mfma_f32_16x16x32_bf16 v[16:19], v[104:107], v[184:187], v[16:19]
	v_mfma_f32_16x16x32_bf16 v[8:11], v[136:139], v[184:187], v[8:11]
	v_mfma_f32_16x16x32_bf16 v[60:63], v[112:115], v[164:167], v[60:63]
	v_mfma_f32_16x16x32_bf16 v[56:59], v[140:143], v[164:167], v[56:59]
	v_mfma_f32_16x16x32_bf16 v[44:47], v[112:115], v[172:175], v[44:47]
	v_mfma_f32_16x16x32_bf16 v[40:43], v[140:143], v[172:175], v[40:43]
	v_mfma_f32_16x16x32_bf16 v[32:35], v[112:115], v[180:183], v[32:35]
	v_mfma_f32_16x16x32_bf16 v[24:27], v[140:143], v[180:183], v[24:27]
	v_mfma_f32_16x16x32_bf16 v[16:19], v[112:115], v[188:191], v[16:19]
	v_mfma_f32_16x16x32_bf16 v[8:11], v[140:143], v[188:191], v[8:11]
	s_setprio 0
	s_setprio 1
	v_mfma_f32_16x16x32_bf16 v[52:55], v[144:147], v[160:163], v[52:55]
	v_mfma_f32_16x16x32_bf16 v[48:51], v[152:155], v[160:163], v[48:51]
	v_mfma_f32_16x16x32_bf16 v[36:39], v[144:147], v[168:171], v[36:39]
	v_mfma_f32_16x16x32_bf16 v[28:31], v[152:155], v[168:171], v[28:31]
	v_mfma_f32_16x16x32_bf16 v[20:23], v[144:147], v[176:179], v[20:23]
	v_mfma_f32_16x16x32_bf16 v[12:15], v[152:155], v[176:179], v[12:15]
	v_mfma_f32_16x16x32_bf16 v[4:7], v[144:147], v[184:187], v[4:7]
	v_mfma_f32_16x16x32_bf16 v[0:3], v[152:155], v[184:187], v[0:3]
	v_mfma_f32_16x16x32_bf16 v[52:55], v[148:151], v[164:167], v[52:55]
	v_mfma_f32_16x16x32_bf16 v[48:51], v[156:159], v[164:167], v[48:51]
	v_mfma_f32_16x16x32_bf16 v[36:39], v[148:151], v[172:175], v[36:39]
	v_mfma_f32_16x16x32_bf16 v[28:31], v[156:159], v[172:175], v[28:31]
	v_mfma_f32_16x16x32_bf16 v[20:23], v[148:151], v[180:183], v[20:23]
	v_mfma_f32_16x16x32_bf16 v[12:15], v[156:159], v[180:183], v[12:15]
	v_mfma_f32_16x16x32_bf16 v[4:7], v[148:151], v[188:191], v[4:7]
	v_mfma_f32_16x16x32_bf16 v[0:3], v[156:159], v[188:191], v[0:3]
	s_setprio 0
	s_barrier
	s_add_i32 s92, s92, 2
	s_add_u32 s44, s44, 0x100
	s_addc_u32 s45, s45, 0
	s_add_u32 s65, s65, 0x100
	s_addc_u32 s81, s81, 0
	s_cmp_gt_u32 s92, 61
	s_cbranch_scc0 .LBB0_209
	s_and_b64 vcc, exec, s[38:39]
	s_cbranch_vccz .LBB0_212
	s_barrier

; #define PG8_STAGE(bufoff, gbase, voff) do { _Pragma("unroll") for (int _i = 0; _i < 2; ++_i) \
;         __builtin_amdgcn_global_load_lds((const unsigned*)((const char*)(gbase) + (voff)[_i]), (LAS unsigned*)(lds + (bufoff) + ldsw + _i * 8192), 16, 0, 0); } while (0)
; #define PG8_LDA(dst, b, h) do { _Pragma("unroll") for (int m = 0; m < 4; ++m) _Pragma("unroll") for (int k = 0; k < 2; ++k) dst[m][k] = *(const LAS bf16x8*)(lds + PG8_SA(b, h) + aoff + m * 2048 + k * 1024); } while (0)
; #define PG8_LDB(dst, b, h) do { _Pragma("unroll") for (int n = 0; n < 2; ++n) _Pragma("unroll") for (int k = 0; k < 2; ++k) dst[n][k] = *(const LAS bf16x8*)(lds + PG8_SB(b, h) + boff + n * 2048 + k * 1024); } while (0)
; #define PG8_MMA(ai, bj, At, Bt) do { __builtin_amdgcn_s_setprio(1); _Pragma("unroll") for (int m = 0; m < 4; ++m) _Pragma("unroll") for (int n = 0; n < 2; ++n) _Pragma("unroll") for (int k = 0; k < 2; ++k) \
;         acc[ai][bj][m][n] = __builtin_amdgcn_mfma_f32_16x16x32_bf16(Bt[n][k], At[m][k], acc[ai][bj][m][n], 0, 0, 0); __builtin_amdgcn_s_setprio(0); } while (0)
; #define PG8_WAIT_V(n) asm volatile("s_waitcnt vmcnt(" #n ")" ::: "memory")
; #define PG8_WAIT_L(n) asm volatile("s_waitcnt lgkmcnt(" #n ")" ::: "memory")
; #define PG8_BAR __builtin_amdgcn_s_barrier()
; #define PG8_SCHED __builtin_amdgcn_sched_barrier(0)
; template <class Epi, class Sched, bool ALIGN_EPI>
; __device__ __forceinline__ void gemm_phase(LAS unsigned char* lds, const Gemm g, const Sched& S, const Epi& E) {
;     ...
;             const char* a1 = cA + (size_t)(t + 1) * kstep;
;             const char* a2 = last ? nA : cA + (size_t)(t + 2) * kstep; const char* b2 = last ? nB : cB + (size_t)(t + 2) * kstep;
;             const char* a3 = a2 + kstep; const char* b3 = b2 + kstep;
;             PG8_LDB(B0, 0, 0); PG8_LDB(B1, 0, 1); PG8_SCHED; PG8_LDA(At, 0, 0); PG8_STAGE(PG8_SA(1, 1), a1 + hstepA, voffA);
;             PG8_WAIT_V(8); PG8_WAIT_L(0); PG8_BAR; PG8_MMA(0, 0, At, B0); PG8_MMA(0, 1, At, B1); PG8_BAR; PG8_SCHED;
;             PG8_LDA(At, 0, 1); PG8_STAGE(PG8_SB(0, 0), b2, voffB); PG8_STAGE(PG8_SB(0, 1), b2 + hstepB, voffB); PG8_STAGE(PG8_SA(0, 0), a2, voffA);
;             PG8_WAIT_V(8); PG8_WAIT_L(0); PG8_BAR; PG8_MMA(1, 0, At, B0); PG8_MMA(1, 1, At, B1); PG8_BAR; PG8_SCHED;
.LBB0_287:
	s_add_u32 s46, s44, 0xfffc0080
	s_addc_u32 s47, s45, -1
	s_add_i32 s92, 0, 0x10000
	s_cmp_eq_u32 s91, 12
	s_cselect_b32 s55, s23, s47
	s_cselect_b32 s54, s85, s46
	s_cselect_b32 s47, s21, s90
	s_cselect_b32 s46, s86, s87
	s_add_i32 s4, 0, 0x14000
	v_add_u32_e32 v132, s92, v160
	v_add_u32_e32 v170, s4, v160
	s_add_i32 m0, s53, 0xc000
	s_nop 0
	global_load_lds_dwordx4 v150, s[44:45]
	s_add_i32 m0, s53, 0xe000
	s_nop 0
	global_load_lds_dwordx4 v152, s[44:45]
	ds_read_b128 v[120:123], v132
	ds_read_b128 v[124:127], v132 offset:1024
	ds_read_b128 v[128:131], v132 offset:2048
	ds_read_b128 v[132:135], v132 offset:3072
	ds_read_b128 v[154:157], v170
	ds_read_b128 v[162:165], v170 offset:1024
	ds_read_b128 v[166:169], v170 offset:2048
	ds_read_b128 v[170:173], v170 offset:3072
	ds_read_b128 v[174:177], v161
	ds_read_b128 v[178:181], v161 offset:1024
	ds_read_b128 v[182:185], v161 offset:2048
	ds_read_b128 v[186:189], v161 offset:3072
	ds_read_b128 v[194:197], v161 offset:4096
	ds_read_b128 v[198:201], v161 offset:5120
	ds_read_b128 v[202:205], v161 offset:6144
	ds_read_b128 v[212:215], v161 offset:7168
	s_waitcnt vmcnt(8)
	s_waitcnt lgkmcnt(0)
	s_barrier
	s_setprio 1
	s_waitcnt lgkmcnt(0)
	v_mfma_f32_16x16x32_bf16 v[140:143], v[120:123], v[174:177], v[140:143]
	v_mfma_f32_16x16x32_bf16 v[136:139], v[128:131], v[174:177], v[136:139]
	v_mfma_f32_16x16x32_bf16 v[108:111], v[120:123], v[182:185], v[108:111]
	v_mfma_f32_16x16x32_bf16 v[104:107], v[128:131], v[182:185], v[104:107]
	v_mfma_f32_16x16x32_bf16 v[92:95], v[120:123], v[194:197], v[92:95]
	v_mfma_f32_16x16x32_bf16 v[88:91], v[128:131], v[194:197], v[88:91]
	v_mfma_f32_16x16x32_bf16 v[76:79], v[120:123], v[202:205], v[76:79]
	v_mfma_f32_16x16x32_bf16 v[72:75], v[128:131], v[202:205], v[72:75]
	v_mfma_f32_16x16x32_bf16 v[140:143], v[124:127], v[178:181], v[140:143]
	v_mfma_f32_16x16x32_bf16 v[136:139], v[132:135], v[178:181], v[136:139]
	v_mfma_f32_16x16x32_bf16 v[108:111], v[124:127], v[186:189], v[108:111]
	v_mfma_f32_16x16x32_bf16 v[104:107], v[132:135], v[186:189], v[104:107]
	v_mfma_f32_16x16x32_bf16 v[92:95], v[124:127], v[198:201], v[92:95]
	v_mfma_f32_16x16x32_bf16 v[88:91], v[132:135], v[198:201], v[88:91]
	v_mfma_f32_16x16x32_bf16 v[76:79], v[124:127], v[212:215], v[76:79]
	v_mfma_f32_16x16x32_bf16 v[72:75], v[132:135], v[212:215], v[72:75]
	s_setprio 0
	s_setprio 1
	v_mfma_f32_16x16x32_bf16 v[116:119], v[154:157], v[174:177], v[116:119]
	v_mfma_f32_16x16x32_bf16 v[112:115], v[166:169], v[174:177], v[112:115]
	v_mfma_f32_16x16x32_bf16 v[100:103], v[154:157], v[182:185], v[100:103]
	v_mfma_f32_16x16x32_bf16 v[96:99], v[166:169], v[182:185], v[96:99]
	v_mfma_f32_16x16x32_bf16 v[84:87], v[154:157], v[194:197], v[84:87]
	v_mfma_f32_16x16x32_bf16 v[80:83], v[166:169], v[194:197], v[80:83]
	v_mfma_f32_16x16x32_bf16 v[68:71], v[154:157], v[202:205], v[68:71]
	v_mfma_f32_16x16x32_bf16 v[64:67], v[166:169], v[202:205], v[64:67]
	v_mfma_f32_16x16x32_bf16 v[116:119], v[162:165], v[178:181], v[116:119]
	v_mfma_f32_16x16x32_bf16 v[112:115], v[170:173], v[178:181], v[112:115]
	v_mfma_f32_16x16x32_bf16 v[100:103], v[162:165], v[186:189], v[100:103]
	v_mfma_f32_16x16x32_bf16 v[96:99], v[170:173], v[186:189], v[96:99]
	v_mfma_f32_16x16x32_bf16 v[84:87], v[162:165], v[198:201], v[84:87]
	v_mfma_f32_16x16x32_bf16 v[80:83], v[170:173], v[198:201], v[80:83]
	v_mfma_f32_16x16x32_bf16 v[68:71], v[162:165], v[212:215], v[68:71]
	v_mfma_f32_16x16x32_bf16 v[64:67], v[170:173], v[212:215], v[64:67]
	s_setprio 0
	s_barrier
	s_add_i32 s5, s92, s52
	s_mov_b32 m0, s53
	s_nop 0
	global_load_lds_dwordx4 v148, s[54:55]
	s_mov_b32 m0, s56
	s_nop 0
	global_load_lds_dwordx4 v146, s[54:55]
	s_mov_b32 m0, s5
	ds_read_b128 v[174:177], v161 offset:16384
	ds_read_b128 v[178:181], v161 offset:17408
	ds_read_b128 v[182:185], v161 offset:18432
	ds_read_b128 v[186:189], v161 offset:19456
	ds_read_b128 v[194:197], v161 offset:20480
	ds_read_b128 v[198:201], v161 offset:21504
	ds_read_b128 v[202:205], v161 offset:22528
	ds_read_b128 v[212:215], v161 offset:23552
	global_load_lds_dwordx4 v192, s[46:47]
	s_add_i32 m0, s5, 0x2000
	s_add_u32 vcc_lo, s46, 0x40000
	s_addc_u32 vcc_hi, s47, 0
	s_add_i32 s4, s4, s52
	global_load_lds_dwordx4 v144, s[46:47]
	s_mov_b32 m0, s4
	s_nop 0
	global_load_lds_dwordx4 v192, vcc
	s_add_i32 m0, s4, 0x2000
	s_nop 0
	global_load_lds_dwordx4 v144, vcc
	s_waitcnt vmcnt(8)
	s_waitcnt lgkmcnt(0)
	s_barrier
	s_setprio 1
	s_waitcnt lgkmcnt(0)
	v_mfma_f32_16x16x32_bf16 v[60:63], v[120:123], v[174:177], v[60:63]
	v_mfma_f32_16x16x32_bf16 v[56:59], v[128:131], v[174:177], v[56:59]
	v_mfma_f32_16x16x32_bf16 v[48:51], v[120:123], v[182:185], v[48:51]
	v_mfma_f32_16x16x32_bf16 v[40:43], v[128:131], v[182:185], v[40:43]
	v_mfma_f32_16x16x32_bf16 v[32:35], v[120:123], v[194:197], v[32:35]
	v_mfma_f32_16x16x32_bf16 v[24:27], v[128:131], v[194:197], v[24:27]
	v_mfma_f32_16x16x32_bf16 v[16:19], v[120:123], v[202:205], v[16:19]
	v_mfma_f32_16x16x32_bf16 v[8:11], v[128:131], v[202:205], v[8:11]
	v_mfma_f32_16x16x32_bf16 v[60:63], v[124:127], v[178:181], v[60:63]
	v_mfma_f32_16x16x32_bf16 v[56:59], v[132:135], v[178:181], v[56:59]
	v_mfma_f32_16x16x32_bf16 v[48:51], v[124:127], v[186:189], v[48:51]
	v_mfma_f32_16x16x32_bf16 v[40:43], v[132:135], v[186:189], v[40:43]
	v_mfma_f32_16x16x32_bf16 v[32:35], v[124:127], v[198:201], v[32:35]
	v_mfma_f32_16x16x32_bf16 v[24:27], v[132:135], v[198:201], v[24:27]
	v_mfma_f32_16x16x32_bf16 v[16:19], v[124:127], v[212:215], v[16:19]
	v_mfma_f32_16x16x32_bf16 v[8:11], v[132:135], v[212:215], v[8:11]
	s_setprio 0
	s_setprio 1
	v_mfma_f32_16x16x32_bf16 v[52:55], v[154:157], v[174:177], v[52:55]
	v_mfma_f32_16x16x32_bf16 v[44:47], v[166:169], v[174:177], v[44:47]
	v_mfma_f32_16x16x32_bf16 v[36:39], v[154:157], v[182:185], v[36:39]
	v_mfma_f32_16x16x32_bf16 v[28:31], v[166:169], v[182:185], v[28:31]
	v_mfma_f32_16x16x32_bf16 v[20:23], v[154:157], v[194:197], v[20:23]
	v_mfma_f32_16x16x32_bf16 v[12:15], v[166:169], v[194:197], v[12:15]
	v_mfma_f32_16x16x32_bf16 v[4:7], v[154:157], v[202:205], v[4:7]
	v_mfma_f32_16x16x32_bf16 v[0:3], v[166:169], v[202:205], v[0:3]
	v_mfma_f32_16x16x32_bf16 v[52:55], v[162:165], v[178:181], v[52:55]
	v_mfma_f32_16x16x32_bf16 v[44:47], v[170:173], v[178:181], v[44:47]
	v_mfma_f32_16x16x32_bf16 v[36:39], v[162:165], v[186:189], v[36:39]
	v_mfma_f32_16x16x32_bf16 v[28:31], v[170:173], v[186:189], v[28:31]
	v_mfma_f32_16x16x32_bf16 v[20:23], v[162:165], v[198:201], v[20:23]
	v_mfma_f32_16x16x32_bf16 v[12:15], v[170:173], v[198:201], v[12:15]
	v_mfma_f32_16x16x32_bf16 v[4:7], v[162:165], v[212:215], v[4:7]
	v_mfma_f32_16x16x32_bf16 v[0:3], v[170:173], v[212:215], v[0:3]
	s_setprio 0
	s_barrier
; #define PG8_STAGE(bufoff, gbase, voff) do { _Pragma("unroll") for (int _i = 0; _i < 2; ++_i) \
;         __builtin_amdgcn_global_load_lds((const unsigned*)((const char*)(gbase) + (voff)[_i]), (LAS unsigned*)(lds + (bufoff) + ldsw + _i * 8192), 16, 0, 0); } while (0)
; #define PG8_LDA(dst, b, h) do { _Pragma("unroll") for (int m = 0; m < 4; ++m) _Pragma("unroll") for (int k = 0; k < 2; ++k) dst[m][k] = *(const LAS bf16x8*)(lds + PG8_SA(b, h) + aoff + m * 2048 + k * 1024); } while (0)
; #define PG8_LDB(dst, b, h) do { _Pragma("unroll") for (int n = 0; n < 2; ++n) _Pragma("unroll") for (int k = 0; k < 2; ++k) dst[n][k] = *(const LAS bf16x8*)(lds + PG8_SB(b, h) + boff + n * 2048 + k * 1024); } while (0)
; #define PG8_MMA(ai, bj, At, Bt) do { __builtin_amdgcn_s_setprio(1); _Pragma("unroll") for (int m = 0; m < 4; ++m) _Pragma("unroll") for (int n = 0; n < 2; ++n) _Pragma("unroll") for (int k = 0; k < 2; ++k) \
;         acc[ai][bj][m][n] = __builtin_amdgcn_mfma_f32_16x16x32_bf16(Bt[n][k], At[m][k], acc[ai][bj][m][n], 0, 0, 0); __builtin_amdgcn_s_setprio(0); } while (0)
; #define PG8_WAIT_V(n) asm volatile("s_waitcnt vmcnt(" #n ")" ::: "memory")
; #define PG8_WAIT_L(n) asm volatile("s_waitcnt lgkmcnt(" #n ")" ::: "memory")
; #define PG8_BAR __builtin_amdgcn_s_barrier()
; #define PG8_SCHED __builtin_amdgcn_sched_barrier(0)
; template <class Epi, class Sched, bool ALIGN_EPI>
; __device__ __forceinline__ void gemm_phase(LAS unsigned char* lds, const Gemm g, const Sched& S, const Epi& E) {
;     ...
;             PG8_LDB(B0, 1, 0); PG8_LDB(B1, 1, 1); PG8_SCHED; PG8_LDA(At, 1, 0); PG8_STAGE(PG8_SA(0, 1), a2 + hstepA, voffA);
;             PG8_WAIT_V(8); PG8_WAIT_L(0); PG8_BAR; PG8_MMA(0, 0, At, B0); PG8_MMA(0, 1, At, B1); PG8_BAR; PG8_SCHED;
;             PG8_LDA(At, 1, 1); PG8_STAGE(PG8_SB(1, 0), b3, voffB); PG8_STAGE(PG8_SB(1, 1), b3 + hstepB, voffB); PG8_STAGE(PG8_SA(1, 0), a3, voffA);
;             PG8_WAIT_V(8); PG8_WAIT_L(0); PG8_BAR; PG8_MMA(1, 0, At, B0); PG8_MMA(1, 1, At, B1); PG8_BAR; PG8_SCHED;
;         }
	s_add_i32 s4, 0, 0x18000
	s_add_i32 s5, 0, 0x1c000
	v_add_u32_e32 v132, s4, v160
	v_add_u32_e32 v170, s5, v160
	s_add_u32 s54, s54, 0x40000
	s_addc_u32 s55, s55, 0
	s_mov_b32 m0, s57
	s_nop 0
	global_load_lds_dwordx4 v148, s[54:55]
	s_mov_b32 m0, s58
	s_nop 0
	global_load_lds_dwordx4 v146, s[54:55]
	ds_read_b128 v[120:123], v132
	ds_read_b128 v[124:127], v132 offset:1024
	ds_read_b128 v[128:131], v132 offset:2048
	ds_read_b128 v[132:135], v132 offset:3072
	ds_read_b128 v[154:157], v170
	ds_read_b128 v[162:165], v170 offset:1024
	ds_read_b128 v[166:169], v170 offset:2048
	ds_read_b128 v[170:173], v170 offset:3072
	ds_read_b128 v[174:177], v161 offset:32768
	ds_read_b128 v[178:181], v161 offset:33792
	ds_read_b128 v[182:185], v161 offset:34816
	ds_read_b128 v[186:189], v161 offset:35840
	ds_read_b128 v[194:197], v161 offset:36864
	ds_read_b128 v[198:201], v161 offset:37888
	ds_read_b128 v[202:205], v161 offset:38912
	ds_read_b128 v[212:215], v161 offset:39936
	s_waitcnt vmcnt(8)
	s_waitcnt lgkmcnt(0)
	s_barrier
	s_setprio 1
	s_waitcnt lgkmcnt(0)
	v_mfma_f32_16x16x32_bf16 v[140:143], v[120:123], v[174:177], v[140:143]
	v_mfma_f32_16x16x32_bf16 v[136:139], v[128:131], v[174:177], v[136:139]
	v_mfma_f32_16x16x32_bf16 v[108:111], v[120:123], v[182:185], v[108:111]
	v_mfma_f32_16x16x32_bf16 v[104:107], v[128:131], v[182:185], v[104:107]
	v_mfma_f32_16x16x32_bf16 v[92:95], v[120:123], v[194:197], v[92:95]
	v_mfma_f32_16x16x32_bf16 v[88:91], v[128:131], v[194:197], v[88:91]
	v_mfma_f32_16x16x32_bf16 v[76:79], v[120:123], v[202:205], v[76:79]
	v_mfma_f32_16x16x32_bf16 v[72:75], v[128:131], v[202:205], v[72:75]
	v_mfma_f32_16x16x32_bf16 v[140:143], v[124:127], v[178:181], v[140:143]
	v_mfma_f32_16x16x32_bf16 v[136:139], v[132:135], v[178:181], v[136:139]
	v_mfma_f32_16x16x32_bf16 v[108:111], v[124:127], v[186:189], v[108:111]
	v_mfma_f32_16x16x32_bf16 v[104:107], v[132:135], v[186:189], v[104:107]
	v_mfma_f32_16x16x32_bf16 v[92:95], v[124:127], v[198:201], v[92:95]
	v_mfma_f32_16x16x32_bf16 v[88:91], v[132:135], v[198:201], v[88:91]
	v_mfma_f32_16x16x32_bf16 v[76:79], v[124:127], v[212:215], v[76:79]
	v_mfma_f32_16x16x32_bf16 v[72:75], v[132:135], v[212:215], v[72:75]
	s_setprio 0
	s_setprio 1
	v_mfma_f32_16x16x32_bf16 v[116:119], v[154:157], v[174:177], v[116:119]
	v_mfma_f32_16x16x32_bf16 v[112:115], v[166:169], v[174:177], v[112:115]
	v_mfma_f32_16x16x32_bf16 v[100:103], v[154:157], v[182:185], v[100:103]
	v_mfma_f32_16x16x32_bf16 v[96:99], v[166:169], v[182:185], v[96:99]
	v_mfma_f32_16x16x32_bf16 v[84:87], v[154:157], v[194:197], v[84:87]
	v_mfma_f32_16x16x32_bf16 v[80:83], v[166:169], v[194:197], v[80:83]
	v_mfma_f32_16x16x32_bf16 v[68:71], v[154:157], v[202:205], v[68:71]
	v_mfma_f32_16x16x32_bf16 v[64:67], v[166:169], v[202:205], v[64:67]
	v_mfma_f32_16x16x32_bf16 v[116:119], v[162:165], v[178:181], v[116:119]
	v_mfma_f32_16x16x32_bf16 v[112:115], v[170:173], v[178:181], v[112:115]
	v_mfma_f32_16x16x32_bf16 v[100:103], v[162:165], v[186:189], v[100:103]
	v_mfma_f32_16x16x32_bf16 v[96:99], v[170:173], v[186:189], v[96:99]
	v_mfma_f32_16x16x32_bf16 v[84:87], v[162:165], v[198:201], v[84:87]
	v_mfma_f32_16x16x32_bf16 v[80:83], v[170:173], v[198:201], v[80:83]
	v_mfma_f32_16x16x32_bf16 v[68:71], v[162:165], v[212:215], v[68:71]
	v_mfma_f32_16x16x32_bf16 v[64:67], v[170:173], v[212:215], v[64:67]
	s_setprio 0
	s_barrier
	s_add_i32 s4, s4, s52
	s_mov_b32 m0, s65
	s_add_u32 s100, s54, 0xfffc0080
	s_addc_u32 s101, s55, -1
	global_load_lds_dwordx4 v148, s[100:101]
	s_mov_b32 m0, s66
	s_nop 0
	global_load_lds_dwordx4 v146, s[100:101]
	s_mov_b32 m0, s4
	ds_read_b128 v[174:177], v161 offset:49152
	ds_read_b128 v[178:181], v161 offset:50176
	ds_read_b128 v[182:185], v161 offset:51200
	ds_read_b128 v[186:189], v161 offset:52224
	ds_read_b128 v[194:197], v161 offset:53248
	ds_read_b128 v[198:201], v161 offset:54272
	ds_read_b128 v[202:205], v161 offset:55296
	ds_read_b128 v[212:215], v161 offset:56320
	s_add_u32 s100, s46, 0x80
	s_addc_u32 s101, s47, 0
	global_load_lds_dwordx4 v192, s[100:101]
	s_add_i32 m0, s4, 0x2000
	s_add_u32 s46, s46, 0x40080
	s_addc_u32 s47, s47, 0
	s_add_i32 s4, s5, s52
	global_load_lds_dwordx4 v144, s[100:101]
	s_mov_b32 m0, s4
	s_nop 0
	global_load_lds_dwordx4 v192, s[46:47]
	s_add_i32 m0, s4, 0x2000
	s_nop 0
	global_load_lds_dwordx4 v144, s[46:47]
	s_waitcnt vmcnt(8)
	s_waitcnt lgkmcnt(0)
	s_barrier
	s_setprio 1
	s_waitcnt lgkmcnt(0)
	v_mfma_f32_16x16x32_bf16 v[60:63], v[120:123], v[174:177], v[60:63]
	v_mfma_f32_16x16x32_bf16 v[56:59], v[128:131], v[174:177], v[56:59]
	v_mfma_f32_16x16x32_bf16 v[48:51], v[120:123], v[182:185], v[48:51]
	v_mfma_f32_16x16x32_bf16 v[40:43], v[128:131], v[182:185], v[40:43]
	v_mfma_f32_16x16x32_bf16 v[32:35], v[120:123], v[194:197], v[32:35]
	v_mfma_f32_16x16x32_bf16 v[24:27], v[128:131], v[194:197], v[24:27]
	v_mfma_f32_16x16x32_bf16 v[16:19], v[120:123], v[202:205], v[16:19]
	v_mfma_f32_16x16x32_bf16 v[8:11], v[128:131], v[202:205], v[8:11]
	v_mfma_f32_16x16x32_bf16 v[60:63], v[124:127], v[178:181], v[60:63]
	v_mfma_f32_16x16x32_bf16 v[56:59], v[132:135], v[178:181], v[56:59]
	v_mfma_f32_16x16x32_bf16 v[48:51], v[124:127], v[186:189], v[48:51]
	v_mfma_f32_16x16x32_bf16 v[40:43], v[132:135], v[186:189], v[40:43]
	v_mfma_f32_16x16x32_bf16 v[32:35], v[124:127], v[198:201], v[32:35]
	v_mfma_f32_16x16x32_bf16 v[24:27], v[132:135], v[198:201], v[24:27]
	v_mfma_f32_16x16x32_bf16 v[16:19], v[124:127], v[212:215], v[16:19]
	v_mfma_f32_16x16x32_bf16 v[8:11], v[132:135], v[212:215], v[8:11]
	s_setprio 0
	s_setprio 1
	v_mfma_f32_16x16x32_bf16 v[52:55], v[154:157], v[174:177], v[52:55]
	v_mfma_f32_16x16x32_bf16 v[44:47], v[166:169], v[174:177], v[44:47]
	v_mfma_f32_16x16x32_bf16 v[36:39], v[154:157], v[182:185], v[36:39]
	v_mfma_f32_16x16x32_bf16 v[28:31], v[166:169], v[182:185], v[28:31]
	v_mfma_f32_16x16x32_bf16 v[20:23], v[154:157], v[194:197], v[20:23]
	v_mfma_f32_16x16x32_bf16 v[12:15], v[166:169], v[194:197], v[12:15]
	v_mfma_f32_16x16x32_bf16 v[4:7], v[154:157], v[202:205], v[4:7]
	v_mfma_f32_16x16x32_bf16 v[0:3], v[166:169], v[202:205], v[0:3]
	v_mfma_f32_16x16x32_bf16 v[52:55], v[162:165], v[178:181], v[52:55]
	v_mfma_f32_16x16x32_bf16 v[44:47], v[170:173], v[178:181], v[44:47]
	v_mfma_f32_16x16x32_bf16 v[36:39], v[162:165], v[186:189], v[36:39]
	v_mfma_f32_16x16x32_bf16 v[28:31], v[170:173], v[186:189], v[28:31]
	v_mfma_f32_16x16x32_bf16 v[20:23], v[162:165], v[198:201], v[20:23]
	v_mfma_f32_16x16x32_bf16 v[12:15], v[170:173], v[198:201], v[12:15]
	v_mfma_f32_16x16x32_bf16 v[4:7], v[162:165], v[212:215], v[4:7]
	v_mfma_f32_16x16x32_bf16 v[0:3], v[170:173], v[212:215], v[0:3]
	s_setprio 0
	s_barrier
	s_add_i32 s91, s91, 2
	s_add_u32 s44, s44, 0x100
	s_addc_u32 s45, s45, 0
	s_add_u32 s87, s87, 0x100
	s_addc_u32 s90, s90, 0
	s_cmp_gt_u32 s91, 13
	s_cbranch_scc0 .LBB0_287
	s_and_b64 vcc, exec, s[16:17]
	s_cbranch_vccz .LBB0_290
	s_barrier

; #define PG8_STAGE(bufoff, gbase, voff) do { _Pragma("unroll") for (int _i = 0; _i < 2; ++_i) \
;         __builtin_amdgcn_global_load_lds((const unsigned*)((const char*)(gbase) + (voff)[_i]), (LAS unsigned*)(lds + (bufoff) + ldsw + _i * 8192), 16, 0, 0); } while (0)
; #define PG8_LDA(dst, b, h) do { _Pragma("unroll") for (int m = 0; m < 4; ++m) _Pragma("unroll") for (int k = 0; k < 2; ++k) dst[m][k] = *(const LAS bf16x8*)(lds + PG8_SA(b, h) + aoff + m * 2048 + k * 1024); } while (0)
; #define PG8_LDB(dst, b, h) do { _Pragma("unroll") for (int n = 0; n < 2; ++n) _Pragma("unroll") for (int k = 0; k < 2; ++k) dst[n][k] = *(const LAS bf16x8*)(lds + PG8_SB(b, h) + boff + n * 2048 + k * 1024); } while (0)
; #define PG8_MMA(ai, bj, At, Bt) do { __builtin_amdgcn_s_setprio(1); _Pragma("unroll") for (int m = 0; m < 4; ++m) _Pragma("unroll") for (int n = 0; n < 2; ++n) _Pragma("unroll") for (int k = 0; k < 2; ++k) \
;         acc[ai][bj][m][n] = __builtin_amdgcn_mfma_f32_16x16x32_bf16(Bt[n][k], At[m][k], acc[ai][bj][m][n], 0, 0, 0); __builtin_amdgcn_s_setprio(0); } while (0)
; #define PG8_WAIT_V(n) asm volatile("s_waitcnt vmcnt(" #n ")" ::: "memory")
; #define PG8_WAIT_L(n) asm volatile("s_waitcnt lgkmcnt(" #n ")" ::: "memory")
; #define PG8_BAR __builtin_amdgcn_s_barrier()
; #define PG8_SCHED __builtin_amdgcn_sched_barrier(0)
; template <class Epi, class Sched, bool ALIGN_EPI>
; __device__ __forceinline__ void gemm_phase(LAS unsigned char* lds, const Gemm g, const Sched& S, const Epi& E) {
;     ...
;             const char* a1 = cA + (size_t)(t + 1) * kstep;
;             const char* a2 = last ? nA : cA + (size_t)(t + 2) * kstep; const char* b2 = last ? nB : cB + (size_t)(t + 2) * kstep;
;             const char* a3 = a2 + kstep; const char* b3 = b2 + kstep;
;             PG8_LDB(B0, 0, 0); PG8_LDB(B1, 0, 1); PG8_SCHED; PG8_LDA(At, 0, 0); PG8_STAGE(PG8_SA(1, 1), a1 + hstepA, voffA);
;             PG8_WAIT_V(8); PG8_WAIT_L(0); PG8_BAR; PG8_MMA(0, 0, At, B0); PG8_MMA(0, 1, At, B1); PG8_BAR; PG8_SCHED;
;             PG8_LDA(At, 0, 1); PG8_STAGE(PG8_SB(0, 0), b2, voffB); PG8_STAGE(PG8_SB(0, 1), b2 + hstepB, voffB); PG8_STAGE(PG8_SA(0, 0), a2, voffA);
;             PG8_WAIT_V(8); PG8_WAIT_L(0); PG8_BAR; PG8_MMA(1, 0, At, B0); PG8_MMA(1, 1, At, B1); PG8_BAR; PG8_SCHED;
.LBB0_316:
	s_add_u32 s46, s44, 0xfffc0080
	s_addc_u32 s47, s45, -1
	s_add_i32 s52, 0, 0x10000
	s_cmp_eq_u32 s92, 12
	s_cselect_b32 s55, s56, s47
	s_cselect_b32 s54, s57, s46
	s_cselect_b32 s47, s59, s65
	s_cselect_b32 s46, s63, s64
	s_add_i32 s53, 0, 0x14000
	v_add_u32_e32 v140, s52, v247
	v_add_u32_e32 v156, s53, v247
	s_add_i32 m0, s48, 0xc000
	s_nop 0
	global_load_lds_dwordx4 v220, s[44:45]
	s_add_i32 m0, s48, 0xe000
	s_nop 0
	global_load_lds_dwordx4 v222, s[44:45]
	ds_read_b128 v[104:107], v140
	ds_read_b128 v[112:115], v140 offset:1024
	ds_read_b128 v[136:139], v140 offset:2048
	ds_read_b128 v[140:143], v140 offset:3072
	ds_read_b128 v[144:147], v156
	ds_read_b128 v[148:151], v156 offset:1024
	ds_read_b128 v[152:155], v156 offset:2048
	ds_read_b128 v[156:159], v156 offset:3072
	ds_read_b128 v[160:163], v248
	ds_read_b128 v[164:167], v248 offset:1024
	ds_read_b128 v[168:171], v248 offset:2048
	ds_read_b128 v[172:175], v248 offset:3072
	ds_read_b128 v[176:179], v248 offset:4096
	ds_read_b128 v[180:183], v248 offset:5120
	ds_read_b128 v[184:187], v248 offset:6144
	ds_read_b128 v[188:191], v248 offset:7168
	s_waitcnt vmcnt(8)
	s_waitcnt lgkmcnt(0)
	s_barrier
	s_setprio 1
	s_waitcnt lgkmcnt(0)
	v_mfma_f32_16x16x32_bf16 v[132:135], v[104:107], v[160:163], v[132:135]
	v_mfma_f32_16x16x32_bf16 v[128:131], v[136:139], v[160:163], v[128:131]
	v_mfma_f32_16x16x32_bf16 v[116:119], v[104:107], v[168:171], v[116:119]
	v_mfma_f32_16x16x32_bf16 v[108:111], v[136:139], v[168:171], v[108:111]
	v_mfma_f32_16x16x32_bf16 v[96:99], v[104:107], v[176:179], v[96:99]
	v_mfma_f32_16x16x32_bf16 v[88:91], v[136:139], v[176:179], v[88:91]
	v_mfma_f32_16x16x32_bf16 v[80:83], v[104:107], v[184:187], v[80:83]
	v_mfma_f32_16x16x32_bf16 v[72:75], v[136:139], v[184:187], v[72:75]
	v_mfma_f32_16x16x32_bf16 v[132:135], v[112:115], v[164:167], v[132:135]
	v_mfma_f32_16x16x32_bf16 v[128:131], v[140:143], v[164:167], v[128:131]
	v_mfma_f32_16x16x32_bf16 v[116:119], v[112:115], v[172:175], v[116:119]
	v_mfma_f32_16x16x32_bf16 v[108:111], v[140:143], v[172:175], v[108:111]
	v_mfma_f32_16x16x32_bf16 v[96:99], v[112:115], v[180:183], v[96:99]
	v_mfma_f32_16x16x32_bf16 v[88:91], v[140:143], v[180:183], v[88:91]
	v_mfma_f32_16x16x32_bf16 v[80:83], v[112:115], v[188:191], v[80:83]
	v_mfma_f32_16x16x32_bf16 v[72:75], v[140:143], v[188:191], v[72:75]
	s_setprio 0
	s_setprio 1
	v_mfma_f32_16x16x32_bf16 v[124:127], v[144:147], v[160:163], v[124:127]
	v_mfma_f32_16x16x32_bf16 v[120:123], v[152:155], v[160:163], v[120:123]
	v_mfma_f32_16x16x32_bf16 v[100:103], v[144:147], v[168:171], v[100:103]
	v_mfma_f32_16x16x32_bf16 v[92:95], v[152:155], v[168:171], v[92:95]
	v_mfma_f32_16x16x32_bf16 v[84:87], v[144:147], v[176:179], v[84:87]
	v_mfma_f32_16x16x32_bf16 v[76:79], v[152:155], v[176:179], v[76:79]
	v_mfma_f32_16x16x32_bf16 v[68:71], v[144:147], v[184:187], v[68:71]
	v_mfma_f32_16x16x32_bf16 v[64:67], v[152:155], v[184:187], v[64:67]
	v_mfma_f32_16x16x32_bf16 v[124:127], v[148:151], v[164:167], v[124:127]
	v_mfma_f32_16x16x32_bf16 v[120:123], v[156:159], v[164:167], v[120:123]
	v_mfma_f32_16x16x32_bf16 v[100:103], v[148:151], v[172:175], v[100:103]
	v_mfma_f32_16x16x32_bf16 v[92:95], v[156:159], v[172:175], v[92:95]
	v_mfma_f32_16x16x32_bf16 v[84:87], v[148:151], v[180:183], v[84:87]
	v_mfma_f32_16x16x32_bf16 v[76:79], v[156:159], v[180:183], v[76:79]
	v_mfma_f32_16x16x32_bf16 v[68:71], v[148:151], v[188:191], v[68:71]
	v_mfma_f32_16x16x32_bf16 v[64:67], v[156:159], v[188:191], v[64:67]
	s_setprio 0
	s_barrier
	s_add_i32 s52, s52, s50
	s_mov_b32 m0, s48
	s_nop 0
	global_load_lds_dwordx4 v218, s[54:55]
	s_mov_b32 m0, s49
	s_nop 0
	global_load_lds_dwordx4 v214, s[54:55]
	s_mov_b32 m0, s52
	ds_read_b128 v[160:163], v248 offset:16384
	ds_read_b128 v[164:167], v248 offset:17408
	ds_read_b128 v[168:171], v248 offset:18432
	ds_read_b128 v[172:175], v248 offset:19456
	ds_read_b128 v[176:179], v248 offset:20480
	ds_read_b128 v[180:183], v248 offset:21504
	ds_read_b128 v[184:187], v248 offset:22528
	ds_read_b128 v[188:191], v248 offset:23552
	global_load_lds_dwordx4 v216, s[46:47]
	s_add_i32 m0, s52, 0x2000
	s_add_u32 vcc_lo, s46, 0x40000
	s_addc_u32 vcc_hi, s47, 0
	s_add_i32 s52, s53, s50
	global_load_lds_dwordx4 v212, s[46:47]
	s_mov_b32 m0, s52
	s_nop 0
	global_load_lds_dwordx4 v216, vcc
	s_add_i32 m0, s52, 0x2000
	s_nop 0
	global_load_lds_dwordx4 v212, vcc
	s_waitcnt vmcnt(8)
	s_waitcnt lgkmcnt(0)
	s_barrier
	s_setprio 1
	s_waitcnt lgkmcnt(0)
	v_mfma_f32_16x16x32_bf16 v[60:63], v[104:107], v[160:163], v[60:63]
	v_mfma_f32_16x16x32_bf16 v[56:59], v[136:139], v[160:163], v[56:59]
	v_mfma_f32_16x16x32_bf16 v[44:47], v[104:107], v[168:171], v[44:47]
	v_mfma_f32_16x16x32_bf16 v[40:43], v[136:139], v[168:171], v[40:43]
	v_mfma_f32_16x16x32_bf16 v[32:35], v[104:107], v[176:179], v[32:35]
	v_mfma_f32_16x16x32_bf16 v[24:27], v[136:139], v[176:179], v[24:27]
	v_mfma_f32_16x16x32_bf16 v[16:19], v[104:107], v[184:187], v[16:19]
	v_mfma_f32_16x16x32_bf16 v[8:11], v[136:139], v[184:187], v[8:11]
	v_mfma_f32_16x16x32_bf16 v[60:63], v[112:115], v[164:167], v[60:63]
	v_mfma_f32_16x16x32_bf16 v[56:59], v[140:143], v[164:167], v[56:59]
	v_mfma_f32_16x16x32_bf16 v[44:47], v[112:115], v[172:175], v[44:47]
	v_mfma_f32_16x16x32_bf16 v[40:43], v[140:143], v[172:175], v[40:43]
	v_mfma_f32_16x16x32_bf16 v[32:35], v[112:115], v[180:183], v[32:35]
	v_mfma_f32_16x16x32_bf16 v[24:27], v[140:143], v[180:183], v[24:27]
	v_mfma_f32_16x16x32_bf16 v[16:19], v[112:115], v[188:191], v[16:19]
	v_mfma_f32_16x16x32_bf16 v[8:11], v[140:143], v[188:191], v[8:11]
	s_setprio 0
	s_setprio 1
	v_mfma_f32_16x16x32_bf16 v[52:55], v[144:147], v[160:163], v[52:55]
	v_mfma_f32_16x16x32_bf16 v[48:51], v[152:155], v[160:163], v[48:51]
	v_mfma_f32_16x16x32_bf16 v[36:39], v[144:147], v[168:171], v[36:39]
	v_mfma_f32_16x16x32_bf16 v[28:31], v[152:155], v[168:171], v[28:31]
	v_mfma_f32_16x16x32_bf16 v[20:23], v[144:147], v[176:179], v[20:23]
	v_mfma_f32_16x16x32_bf16 v[12:15], v[152:155], v[176:179], v[12:15]
	v_mfma_f32_16x16x32_bf16 v[4:7], v[144:147], v[184:187], v[4:7]
	v_mfma_f32_16x16x32_bf16 v[0:3], v[152:155], v[184:187], v[0:3]
	v_mfma_f32_16x16x32_bf16 v[52:55], v[148:151], v[164:167], v[52:55]
	v_mfma_f32_16x16x32_bf16 v[48:51], v[156:159], v[164:167], v[48:51]
	v_mfma_f32_16x16x32_bf16 v[36:39], v[148:151], v[172:175], v[36:39]
	v_mfma_f32_16x16x32_bf16 v[28:31], v[156:159], v[172:175], v[28:31]
	v_mfma_f32_16x16x32_bf16 v[20:23], v[148:151], v[180:183], v[20:23]
	v_mfma_f32_16x16x32_bf16 v[12:15], v[156:159], v[180:183], v[12:15]
	v_mfma_f32_16x16x32_bf16 v[4:7], v[148:151], v[188:191], v[4:7]
	v_mfma_f32_16x16x32_bf16 v[0:3], v[156:159], v[188:191], v[0:3]
	s_setprio 0
	s_barrier
; #define PG8_STAGE(bufoff, gbase, voff) do { _Pragma("unroll") for (int _i = 0; _i < 2; ++_i) \
;         __builtin_amdgcn_global_load_lds((const unsigned*)((const char*)(gbase) + (voff)[_i]), (LAS unsigned*)(lds + (bufoff) + ldsw + _i * 8192), 16, 0, 0); } while (0)
; #define PG8_LDA(dst, b, h) do { _Pragma("unroll") for (int m = 0; m < 4; ++m) _Pragma("unroll") for (int k = 0; k < 2; ++k) dst[m][k] = *(const LAS bf16x8*)(lds + PG8_SA(b, h) + aoff + m * 2048 + k * 1024); } while (0)
; #define PG8_LDB(dst, b, h) do { _Pragma("unroll") for (int n = 0; n < 2; ++n) _Pragma("unroll") for (int k = 0; k < 2; ++k) dst[n][k] = *(const LAS bf16x8*)(lds + PG8_SB(b, h) + boff + n * 2048 + k * 1024); } while (0)
; #define PG8_MMA(ai, bj, At, Bt) do { __builtin_amdgcn_s_setprio(1); _Pragma("unroll") for (int m = 0; m < 4; ++m) _Pragma("unroll") for (int n = 0; n < 2; ++n) _Pragma("unroll") for (int k = 0; k < 2; ++k) \
;         acc[ai][bj][m][n] = __builtin_amdgcn_mfma_f32_16x16x32_bf16(Bt[n][k], At[m][k], acc[ai][bj][m][n], 0, 0, 0); __builtin_amdgcn_s_setprio(0); } while (0)
; #define PG8_WAIT_V(n) asm volatile("s_waitcnt vmcnt(" #n ")" ::: "memory")
; #define PG8_WAIT_L(n) asm volatile("s_waitcnt lgkmcnt(" #n ")" ::: "memory")
; #define PG8_BAR __builtin_amdgcn_s_barrier()
; #define PG8_SCHED __builtin_amdgcn_sched_barrier(0)
; template <class Epi, class Sched, bool ALIGN_EPI>
; __device__ __forceinline__ void gemm_phase(LAS unsigned char* lds, const Gemm g, const Sched& S, const Epi& E) {
;     ...
;             PG8_LDB(B0, 1, 0); PG8_LDB(B1, 1, 1); PG8_SCHED; PG8_LDA(At, 1, 0); PG8_STAGE(PG8_SA(0, 1), a2 + hstepA, voffA);
;             PG8_WAIT_V(8); PG8_WAIT_L(0); PG8_BAR; PG8_MMA(0, 0, At, B0); PG8_MMA(0, 1, At, B1); PG8_BAR; PG8_SCHED;
;             PG8_LDA(At, 1, 1); PG8_STAGE(PG8_SB(1, 0), b3, voffB); PG8_STAGE(PG8_SB(1, 1), b3 + hstepB, voffB); PG8_STAGE(PG8_SA(1, 0), a3, voffA);
;             PG8_WAIT_V(8); PG8_WAIT_L(0); PG8_BAR; PG8_MMA(1, 0, At, B0); PG8_MMA(1, 1, At, B1); PG8_BAR; PG8_SCHED;
;         }
	s_add_i32 s52, 0, 0x18000
	s_add_i32 s53, 0, 0x1c000
	v_add_u32_e32 v140, s52, v247
	v_add_u32_e32 v156, s53, v247
	s_add_u32 s54, s54, 0x40000
	s_addc_u32 s55, s55, 0
	s_mov_b32 m0, s67
	s_nop 0
	global_load_lds_dwordx4 v218, s[54:55]
	s_mov_b32 m0, s90
	s_nop 0
	global_load_lds_dwordx4 v214, s[54:55]
	ds_read_b128 v[104:107], v140
	ds_read_b128 v[112:115], v140 offset:1024
	ds_read_b128 v[136:139], v140 offset:2048
	ds_read_b128 v[140:143], v140 offset:3072
	ds_read_b128 v[144:147], v156
	ds_read_b128 v[148:151], v156 offset:1024
	ds_read_b128 v[152:155], v156 offset:2048
	ds_read_b128 v[156:159], v156 offset:3072
	ds_read_b128 v[160:163], v248 offset:32768
	ds_read_b128 v[164:167], v248 offset:33792
	ds_read_b128 v[168:171], v248 offset:34816
	ds_read_b128 v[172:175], v248 offset:35840
	ds_read_b128 v[176:179], v248 offset:36864
	ds_read_b128 v[180:183], v248 offset:37888
	ds_read_b128 v[184:187], v248 offset:38912
	ds_read_b128 v[188:191], v248 offset:39936
	s_waitcnt vmcnt(8)
	s_waitcnt lgkmcnt(0)
	s_barrier
	s_setprio 1
	s_waitcnt lgkmcnt(0)
	v_mfma_f32_16x16x32_bf16 v[132:135], v[104:107], v[160:163], v[132:135]
	v_mfma_f32_16x16x32_bf16 v[128:131], v[136:139], v[160:163], v[128:131]
	v_mfma_f32_16x16x32_bf16 v[116:119], v[104:107], v[168:171], v[116:119]
	v_mfma_f32_16x16x32_bf16 v[108:111], v[136:139], v[168:171], v[108:111]
	v_mfma_f32_16x16x32_bf16 v[96:99], v[104:107], v[176:179], v[96:99]
	v_mfma_f32_16x16x32_bf16 v[88:91], v[136:139], v[176:179], v[88:91]
	v_mfma_f32_16x16x32_bf16 v[80:83], v[104:107], v[184:187], v[80:83]
	v_mfma_f32_16x16x32_bf16 v[72:75], v[136:139], v[184:187], v[72:75]
	v_mfma_f32_16x16x32_bf16 v[132:135], v[112:115], v[164:167], v[132:135]
	v_mfma_f32_16x16x32_bf16 v[128:131], v[140:143], v[164:167], v[128:131]
	v_mfma_f32_16x16x32_bf16 v[116:119], v[112:115], v[172:175], v[116:119]
	v_mfma_f32_16x16x32_bf16 v[108:111], v[140:143], v[172:175], v[108:111]
	v_mfma_f32_16x16x32_bf16 v[96:99], v[112:115], v[180:183], v[96:99]
	v_mfma_f32_16x16x32_bf16 v[88:91], v[140:143], v[180:183], v[88:91]
	v_mfma_f32_16x16x32_bf16 v[80:83], v[112:115], v[188:191], v[80:83]
	v_mfma_f32_16x16x32_bf16 v[72:75], v[140:143], v[188:191], v[72:75]
	s_setprio 0
	s_setprio 1
	v_mfma_f32_16x16x32_bf16 v[124:127], v[144:147], v[160:163], v[124:127]
	v_mfma_f32_16x16x32_bf16 v[120:123], v[152:155], v[160:163], v[120:123]
	v_mfma_f32_16x16x32_bf16 v[100:103], v[144:147], v[168:171], v[100:103]
	v_mfma_f32_16x16x32_bf16 v[92:95], v[152:155], v[168:171], v[92:95]
	v_mfma_f32_16x16x32_bf16 v[84:87], v[144:147], v[176:179], v[84:87]
	v_mfma_f32_16x16x32_bf16 v[76:79], v[152:155], v[176:179], v[76:79]
	v_mfma_f32_16x16x32_bf16 v[68:71], v[144:147], v[184:187], v[68:71]
	v_mfma_f32_16x16x32_bf16 v[64:67], v[152:155], v[184:187], v[64:67]
	v_mfma_f32_16x16x32_bf16 v[124:127], v[148:151], v[164:167], v[124:127]
	v_mfma_f32_16x16x32_bf16 v[120:123], v[156:159], v[164:167], v[120:123]
	v_mfma_f32_16x16x32_bf16 v[100:103], v[148:151], v[172:175], v[100:103]
	v_mfma_f32_16x16x32_bf16 v[92:95], v[156:159], v[172:175], v[92:95]
	v_mfma_f32_16x16x32_bf16 v[84:87], v[148:151], v[180:183], v[84:87]
	v_mfma_f32_16x16x32_bf16 v[76:79], v[156:159], v[180:183], v[76:79]
	v_mfma_f32_16x16x32_bf16 v[68:71], v[148:151], v[188:191], v[68:71]
	v_mfma_f32_16x16x32_bf16 v[64:67], v[156:159], v[188:191], v[64:67]
	s_setprio 0
	s_barrier
	s_add_i32 s52, s52, s50
	s_mov_b32 m0, s66
	s_add_u32 s100, s54, 0xfffc0080
	s_addc_u32 s101, s55, -1
	global_load_lds_dwordx4 v218, s[100:101]
	s_mov_b32 m0, s86
	s_nop 0
	global_load_lds_dwordx4 v214, s[100:101]
	s_mov_b32 m0, s52
	ds_read_b128 v[160:163], v248 offset:49152
	ds_read_b128 v[164:167], v248 offset:50176
	ds_read_b128 v[168:171], v248 offset:51200
	ds_read_b128 v[172:175], v248 offset:52224
	ds_read_b128 v[176:179], v248 offset:53248
	ds_read_b128 v[180:183], v248 offset:54272
	ds_read_b128 v[184:187], v248 offset:55296
	ds_read_b128 v[188:191], v248 offset:56320
	s_add_u32 s100, s46, 0x80
	s_addc_u32 s101, s47, 0
	global_load_lds_dwordx4 v216, s[100:101]
	s_add_i32 m0, s52, 0x2000
	s_add_u32 s46, s46, 0x40080
	s_addc_u32 s47, s47, 0
	s_add_i32 s52, s53, s50
	global_load_lds_dwordx4 v212, s[100:101]
	s_mov_b32 m0, s52
	s_nop 0
	global_load_lds_dwordx4 v216, s[46:47]
	s_add_i32 m0, s52, 0x2000
	s_nop 0
	global_load_lds_dwordx4 v212, s[46:47]
	s_waitcnt vmcnt(8)
	s_waitcnt lgkmcnt(0)
	s_barrier
	s_setprio 1
	s_waitcnt lgkmcnt(0)
	v_mfma_f32_16x16x32_bf16 v[60:63], v[104:107], v[160:163], v[60:63]
	v_mfma_f32_16x16x32_bf16 v[56:59], v[136:139], v[160:163], v[56:59]
	v_mfma_f32_16x16x32_bf16 v[44:47], v[104:107], v[168:171], v[44:47]
	v_mfma_f32_16x16x32_bf16 v[40:43], v[136:139], v[168:171], v[40:43]
	v_mfma_f32_16x16x32_bf16 v[32:35], v[104:107], v[176:179], v[32:35]
	v_mfma_f32_16x16x32_bf16 v[24:27], v[136:139], v[176:179], v[24:27]
	v_mfma_f32_16x16x32_bf16 v[16:19], v[104:107], v[184:187], v[16:19]
	v_mfma_f32_16x16x32_bf16 v[8:11], v[136:139], v[184:187], v[8:11]
	v_mfma_f32_16x16x32_bf16 v[60:63], v[112:115], v[164:167], v[60:63]
	v_mfma_f32_16x16x32_bf16 v[56:59], v[140:143], v[164:167], v[56:59]
	v_mfma_f32_16x16x32_bf16 v[44:47], v[112:115], v[172:175], v[44:47]
	v_mfma_f32_16x16x32_bf16 v[40:43], v[140:143], v[172:175], v[40:43]
	v_mfma_f32_16x16x32_bf16 v[32:35], v[112:115], v[180:183], v[32:35]
	v_mfma_f32_16x16x32_bf16 v[24:27], v[140:143], v[180:183], v[24:27]
	v_mfma_f32_16x16x32_bf16 v[16:19], v[112:115], v[188:191], v[16:19]
	v_mfma_f32_16x16x32_bf16 v[8:11], v[140:143], v[188:191], v[8:11]
	s_setprio 0
	s_setprio 1
	v_mfma_f32_16x16x32_bf16 v[52:55], v[144:147], v[160:163], v[52:55]
	v_mfma_f32_16x16x32_bf16 v[48:51], v[152:155], v[160:163], v[48:51]
	v_mfma_f32_16x16x32_bf16 v[36:39], v[144:147], v[168:171], v[36:39]
	v_mfma_f32_16x16x32_bf16 v[28:31], v[152:155], v[168:171], v[28:31]
	v_mfma_f32_16x16x32_bf16 v[20:23], v[144:147], v[176:179], v[20:23]
	v_mfma_f32_16x16x32_bf16 v[12:15], v[152:155], v[176:179], v[12:15]
	v_mfma_f32_16x16x32_bf16 v[4:7], v[144:147], v[184:187], v[4:7]
	v_mfma_f32_16x16x32_bf16 v[0:3], v[152:155], v[184:187], v[0:3]
	v_mfma_f32_16x16x32_bf16 v[52:55], v[148:151], v[164:167], v[52:55]
	v_mfma_f32_16x16x32_bf16 v[48:51], v[156:159], v[164:167], v[48:51]
	v_mfma_f32_16x16x32_bf16 v[36:39], v[148:151], v[172:175], v[36:39]
	v_mfma_f32_16x16x32_bf16 v[28:31], v[156:159], v[172:175], v[28:31]
	v_mfma_f32_16x16x32_bf16 v[20:23], v[148:151], v[180:183], v[20:23]
	v_mfma_f32_16x16x32_bf16 v[12:15], v[156:159], v[180:183], v[12:15]
	v_mfma_f32_16x16x32_bf16 v[4:7], v[148:151], v[188:191], v[4:7]
	v_mfma_f32_16x16x32_bf16 v[0:3], v[156:159], v[188:191], v[0:3]
	s_setprio 0
	s_barrier
	s_add_i32 s92, s92, 2
	s_add_u32 s44, s44, 0x100
	s_addc_u32 s45, s45, 0
	s_add_u32 s64, s64, 0x100
	s_addc_u32 s65, s65, 0
	s_cmp_gt_u32 s92, 13
	s_cbranch_scc0 .LBB0_316
	s_and_b64 vcc, exec, s[22:23]
	s_cbranch_vccz .LBB0_319
	s_barrier

; #define PG8_STAGE(bufoff, gbase, voff) do { _Pragma("unroll") for (int _i = 0; _i < 2; ++_i) \
;         __builtin_amdgcn_global_load_lds((const unsigned*)((const char*)(gbase) + (voff)[_i]), (LAS unsigned*)(lds + (bufoff) + ldsw + _i * 8192), 16, 0, 0); } while (0)
; #define PG8_LDA(dst, b, h) do { _Pragma("unroll") for (int m = 0; m < 4; ++m) _Pragma("unroll") for (int k = 0; k < 2; ++k) dst[m][k] = *(const LAS bf16x8*)(lds + PG8_SA(b, h) + aoff + m * 2048 + k * 1024); } while (0)
; #define PG8_LDB(dst, b, h) do { _Pragma("unroll") for (int n = 0; n < 2; ++n) _Pragma("unroll") for (int k = 0; k < 2; ++k) dst[n][k] = *(const LAS bf16x8*)(lds + PG8_SB(b, h) + boff + n * 2048 + k * 1024); } while (0)
; #define PG8_MMA(ai, bj, At, Bt) do { __builtin_amdgcn_s_setprio(1); _Pragma("unroll") for (int m = 0; m < 4; ++m) _Pragma("unroll") for (int n = 0; n < 2; ++n) _Pragma("unroll") for (int k = 0; k < 2; ++k) \
;         acc[ai][bj][m][n] = __builtin_amdgcn_mfma_f32_16x16x32_bf16(Bt[n][k], At[m][k], acc[ai][bj][m][n], 0, 0, 0); __builtin_amdgcn_s_setprio(0); } while (0)
; #define PG8_WAIT_V(n) asm volatile("s_waitcnt vmcnt(" #n ")" ::: "memory")
; #define PG8_WAIT_L(n) asm volatile("s_waitcnt lgkmcnt(" #n ")" ::: "memory")
; #define PG8_BAR __builtin_amdgcn_s_barrier()
; #define PG8_SCHED __builtin_amdgcn_sched_barrier(0)
; template <class Epi, class Sched, bool ALIGN_EPI>
; __device__ __forceinline__ void gemm_phase(LAS unsigned char* lds, const Gemm g, const Sched& S, const Epi& E) {
;     ...
;             const char* a1 = cA + (size_t)(t + 1) * kstep;
;             const char* a2 = last ? nA : cA + (size_t)(t + 2) * kstep; const char* b2 = last ? nB : cB + (size_t)(t + 2) * kstep;
;             const char* a3 = a2 + kstep; const char* b3 = b2 + kstep;
;             PG8_LDB(B0, 0, 0); PG8_LDB(B1, 0, 1); PG8_SCHED; PG8_LDA(At, 0, 0); PG8_STAGE(PG8_SA(1, 1), a1 + hstepA, voffA);
;             PG8_WAIT_V(8); PG8_WAIT_L(0); PG8_BAR; PG8_MMA(0, 0, At, B0); PG8_MMA(0, 1, At, B1); PG8_BAR; PG8_SCHED;
;             PG8_LDA(At, 0, 1); PG8_STAGE(PG8_SB(0, 0), b2, voffB); PG8_STAGE(PG8_SB(0, 1), b2 + hstepB, voffB); PG8_STAGE(PG8_SA(0, 0), a2, voffA);
;             PG8_WAIT_V(8); PG8_WAIT_L(0); PG8_BAR; PG8_MMA(1, 0, At, B0); PG8_MMA(1, 1, At, B1); PG8_BAR; PG8_SCHED;
.LBB0_388:
	s_add_u32 s42, s44, 0xfffe0080
	s_addc_u32 s43, s45, -1
	s_add_i32 vcc_hi, 0, 0x10000
	s_cmp_eq_u32 vcc_lo, 4
	s_cselect_b32 s57, s85, s43
	s_cselect_b32 s56, s86, s42
	s_cselect_b32 s55, s87, s92
	s_cselect_b32 s54, s90, s91
	s_add_i32 s8, 0, 0x14000
	v_add_u32_e32 v140, vcc_hi, v184
	v_add_u32_e32 v156, s8, v184
	s_add_i32 m0, s53, 0xc000
	s_nop 0
	global_load_lds_dwordx4 v166, s[44:45]
	s_add_i32 m0, s53, 0xe000
	s_nop 0
	global_load_lds_dwordx4 v168, s[44:45]
	ds_read_b128 v[72:75], v140
	ds_read_b128 v[76:79], v140 offset:1024
	ds_read_b128 v[136:139], v140 offset:2048
	ds_read_b128 v[140:143], v140 offset:3072
	ds_read_b128 v[144:147], v156
	ds_read_b128 v[148:151], v156 offset:1024
	ds_read_b128 v[152:155], v156 offset:2048
	ds_read_b128 v[156:159], v156 offset:3072
	ds_read_b128 v[170:173], v185
	ds_read_b128 v[174:177], v185 offset:1024
	ds_read_b128 v[178:181], v185 offset:2048
	ds_read_b128 v[186:189], v185 offset:3072
	ds_read_b128 v[194:197], v185 offset:4096
	ds_read_b128 v[198:201], v185 offset:5120
	ds_read_b128 v[202:205], v185 offset:6144
	ds_read_b128 v[212:215], v185 offset:7168
	s_waitcnt vmcnt(8)
	s_waitcnt lgkmcnt(0)
	s_barrier
	s_setprio 1
	s_waitcnt lgkmcnt(0)
	v_mfma_f32_16x16x32_bf16 v[64:67], v[72:75], v[170:173], v[64:67]
	v_mfma_f32_16x16x32_bf16 v[60:63], v[136:139], v[170:173], v[60:63]
	v_mfma_f32_16x16x32_bf16 v[124:127], v[72:75], v[178:181], v[124:127]
	v_mfma_f32_16x16x32_bf16 v[120:123], v[136:139], v[178:181], v[120:123]
	v_mfma_f32_16x16x32_bf16 v[108:111], v[72:75], v[194:197], v[108:111]
	v_mfma_f32_16x16x32_bf16 v[104:107], v[136:139], v[194:197], v[104:107]
	v_mfma_f32_16x16x32_bf16 v[92:95], v[72:75], v[202:205], v[92:95]
	v_mfma_f32_16x16x32_bf16 v[88:91], v[136:139], v[202:205], v[88:91]
	v_mfma_f32_16x16x32_bf16 v[64:67], v[76:79], v[174:177], v[64:67]
	v_mfma_f32_16x16x32_bf16 v[60:63], v[140:143], v[174:177], v[60:63]
	v_mfma_f32_16x16x32_bf16 v[124:127], v[76:79], v[186:189], v[124:127]
	v_mfma_f32_16x16x32_bf16 v[120:123], v[140:143], v[186:189], v[120:123]
	v_mfma_f32_16x16x32_bf16 v[108:111], v[76:79], v[198:201], v[108:111]
	v_mfma_f32_16x16x32_bf16 v[104:107], v[140:143], v[198:201], v[104:107]
	v_mfma_f32_16x16x32_bf16 v[92:95], v[76:79], v[212:215], v[92:95]
	v_mfma_f32_16x16x32_bf16 v[88:91], v[140:143], v[212:215], v[88:91]
	s_setprio 0
	s_setprio 1
	v_mfma_f32_16x16x32_bf16 v[132:135], v[144:147], v[170:173], v[132:135]
	v_mfma_f32_16x16x32_bf16 v[128:131], v[152:155], v[170:173], v[128:131]
	v_mfma_f32_16x16x32_bf16 v[116:119], v[144:147], v[178:181], v[116:119]
	v_mfma_f32_16x16x32_bf16 v[112:115], v[152:155], v[178:181], v[112:115]
	v_mfma_f32_16x16x32_bf16 v[100:103], v[144:147], v[194:197], v[100:103]
	v_mfma_f32_16x16x32_bf16 v[96:99], v[152:155], v[194:197], v[96:99]
	v_mfma_f32_16x16x32_bf16 v[84:87], v[144:147], v[202:205], v[84:87]
	v_mfma_f32_16x16x32_bf16 v[80:83], v[152:155], v[202:205], v[80:83]
	v_mfma_f32_16x16x32_bf16 v[132:135], v[148:151], v[174:177], v[132:135]
	v_mfma_f32_16x16x32_bf16 v[128:131], v[156:159], v[174:177], v[128:131]
	v_mfma_f32_16x16x32_bf16 v[116:119], v[148:151], v[186:189], v[116:119]
	v_mfma_f32_16x16x32_bf16 v[112:115], v[156:159], v[186:189], v[112:115]
	v_mfma_f32_16x16x32_bf16 v[100:103], v[148:151], v[198:201], v[100:103]
	v_mfma_f32_16x16x32_bf16 v[96:99], v[156:159], v[198:201], v[96:99]
	v_mfma_f32_16x16x32_bf16 v[84:87], v[148:151], v[212:215], v[84:87]
	v_mfma_f32_16x16x32_bf16 v[80:83], v[156:159], v[212:215], v[80:83]
	s_setprio 0
	s_barrier
	s_add_i32 s9, vcc_hi, s52
	s_mov_b32 m0, s53
	s_nop 0
	global_load_lds_dwordx4 v164, s[56:57]
	s_mov_b32 m0, s58
	s_nop 0
	global_load_lds_dwordx4 v162, s[56:57]
	s_mov_b32 m0, s9
	ds_read_b128 v[170:173], v185 offset:16384
	ds_read_b128 v[174:177], v185 offset:17408
	ds_read_b128 v[178:181], v185 offset:18432
	ds_read_b128 v[186:189], v185 offset:19456
	ds_read_b128 v[194:197], v185 offset:20480
	ds_read_b128 v[198:201], v185 offset:21504
	ds_read_b128 v[202:205], v185 offset:22528
	ds_read_b128 v[212:215], v185 offset:23552
	global_load_lds_dwordx4 v192, s[54:55]
	s_add_i32 m0, s9, 0x2000
	s_add_u32 s42, s54, 0x20000
	s_addc_u32 s43, s55, 0
	s_add_i32 s8, s8, s52
	global_load_lds_dwordx4 v160, s[54:55]
	s_mov_b32 m0, s8
	s_nop 0
	global_load_lds_dwordx4 v192, s[42:43]
	s_add_i32 m0, s8, 0x2000
	s_nop 0
	global_load_lds_dwordx4 v160, s[42:43]
	s_waitcnt vmcnt(8)
	s_waitcnt lgkmcnt(0)
	s_barrier
	s_setprio 1
	s_waitcnt lgkmcnt(0)
	v_mfma_f32_16x16x32_bf16 v[68:71], v[72:75], v[170:173], v[68:71]
	v_mfma_f32_16x16x32_bf16 v[56:59], v[136:139], v[170:173], v[56:59]
	v_mfma_f32_16x16x32_bf16 v[44:47], v[72:75], v[178:181], v[44:47]
	v_mfma_f32_16x16x32_bf16 v[40:43], v[136:139], v[178:181], v[40:43]
	v_mfma_f32_16x16x32_bf16 v[28:31], v[72:75], v[194:197], v[28:31]
	v_mfma_f32_16x16x32_bf16 v[24:27], v[136:139], v[194:197], v[24:27]
	v_mfma_f32_16x16x32_bf16 v[12:15], v[72:75], v[202:205], v[12:15]
	v_mfma_f32_16x16x32_bf16 v[8:11], v[136:139], v[202:205], v[8:11]
	v_mfma_f32_16x16x32_bf16 v[68:71], v[76:79], v[174:177], v[68:71]
	v_mfma_f32_16x16x32_bf16 v[56:59], v[140:143], v[174:177], v[56:59]
	v_mfma_f32_16x16x32_bf16 v[44:47], v[76:79], v[186:189], v[44:47]
	v_mfma_f32_16x16x32_bf16 v[40:43], v[140:143], v[186:189], v[40:43]
	v_mfma_f32_16x16x32_bf16 v[28:31], v[76:79], v[198:201], v[28:31]
	v_mfma_f32_16x16x32_bf16 v[24:27], v[140:143], v[198:201], v[24:27]
	v_mfma_f32_16x16x32_bf16 v[12:15], v[76:79], v[212:215], v[12:15]
	v_mfma_f32_16x16x32_bf16 v[8:11], v[140:143], v[212:215], v[8:11]
	s_setprio 0
	s_setprio 1
	v_mfma_f32_16x16x32_bf16 v[52:55], v[144:147], v[170:173], v[52:55]
	v_mfma_f32_16x16x32_bf16 v[48:51], v[152:155], v[170:173], v[48:51]
	v_mfma_f32_16x16x32_bf16 v[36:39], v[144:147], v[178:181], v[36:39]
	v_mfma_f32_16x16x32_bf16 v[32:35], v[152:155], v[178:181], v[32:35]
	v_mfma_f32_16x16x32_bf16 v[20:23], v[144:147], v[194:197], v[20:23]
	v_mfma_f32_16x16x32_bf16 v[16:19], v[152:155], v[194:197], v[16:19]
	v_mfma_f32_16x16x32_bf16 v[4:7], v[144:147], v[202:205], v[4:7]
	v_mfma_f32_16x16x32_bf16 v[0:3], v[152:155], v[202:205], v[0:3]
	v_mfma_f32_16x16x32_bf16 v[52:55], v[148:151], v[174:177], v[52:55]
	v_mfma_f32_16x16x32_bf16 v[48:51], v[156:159], v[174:177], v[48:51]
	v_mfma_f32_16x16x32_bf16 v[36:39], v[148:151], v[186:189], v[36:39]
	v_mfma_f32_16x16x32_bf16 v[32:35], v[156:159], v[186:189], v[32:35]
	v_mfma_f32_16x16x32_bf16 v[20:23], v[148:151], v[198:201], v[20:23]
	v_mfma_f32_16x16x32_bf16 v[16:19], v[156:159], v[198:201], v[16:19]
	v_mfma_f32_16x16x32_bf16 v[4:7], v[148:151], v[212:215], v[4:7]
	v_mfma_f32_16x16x32_bf16 v[0:3], v[156:159], v[212:215], v[0:3]
	s_setprio 0
	s_barrier
; #define PG8_STAGE(bufoff, gbase, voff) do { _Pragma("unroll") for (int _i = 0; _i < 2; ++_i) \
;         __builtin_amdgcn_global_load_lds((const unsigned*)((const char*)(gbase) + (voff)[_i]), (LAS unsigned*)(lds + (bufoff) + ldsw + _i * 8192), 16, 0, 0); } while (0)
; #define PG8_LDA(dst, b, h) do { _Pragma("unroll") for (int m = 0; m < 4; ++m) _Pragma("unroll") for (int k = 0; k < 2; ++k) dst[m][k] = *(const LAS bf16x8*)(lds + PG8_SA(b, h) + aoff + m * 2048 + k * 1024); } while (0)
; #define PG8_LDB(dst, b, h) do { _Pragma("unroll") for (int n = 0; n < 2; ++n) _Pragma("unroll") for (int k = 0; k < 2; ++k) dst[n][k] = *(const LAS bf16x8*)(lds + PG8_SB(b, h) + boff + n * 2048 + k * 1024); } while (0)
; #define PG8_MMA(ai, bj, At, Bt) do { __builtin_amdgcn_s_setprio(1); _Pragma("unroll") for (int m = 0; m < 4; ++m) _Pragma("unroll") for (int n = 0; n < 2; ++n) _Pragma("unroll") for (int k = 0; k < 2; ++k) \
;         acc[ai][bj][m][n] = __builtin_amdgcn_mfma_f32_16x16x32_bf16(Bt[n][k], At[m][k], acc[ai][bj][m][n], 0, 0, 0); __builtin_amdgcn_s_setprio(0); } while (0)
; #define PG8_WAIT_V(n) asm volatile("s_waitcnt vmcnt(" #n ")" ::: "memory")
; #define PG8_WAIT_L(n) asm volatile("s_waitcnt lgkmcnt(" #n ")" ::: "memory")
; #define PG8_BAR __builtin_amdgcn_s_barrier()
; #define PG8_SCHED __builtin_amdgcn_sched_barrier(0)
; template <class Epi, class Sched, bool ALIGN_EPI>
; __device__ __forceinline__ void gemm_phase(LAS unsigned char* lds, const Gemm g, const Sched& S, const Epi& E) {
;     ...
;             PG8_LDB(B0, 1, 0); PG8_LDB(B1, 1, 1); PG8_SCHED; PG8_LDA(At, 1, 0); PG8_STAGE(PG8_SA(0, 1), a2 + hstepA, voffA);
;             PG8_WAIT_V(8); PG8_WAIT_L(0); PG8_BAR; PG8_MMA(0, 0, At, B0); PG8_MMA(0, 1, At, B1); PG8_BAR; PG8_SCHED;
;             PG8_LDA(At, 1, 1); PG8_STAGE(PG8_SB(1, 0), b3, voffB); PG8_STAGE(PG8_SB(1, 1), b3 + hstepB, voffB); PG8_STAGE(PG8_SA(1, 0), a3, voffA);
;             PG8_WAIT_V(8); PG8_WAIT_L(0); PG8_BAR; PG8_MMA(1, 0, At, B0); PG8_MMA(1, 1, At, B1); PG8_BAR; PG8_SCHED;
;         }
	s_add_i32 s8, 0, 0x18000
	s_add_i32 s9, 0, 0x1c000
	v_add_u32_e32 v140, s8, v184
	v_add_u32_e32 v156, s9, v184
	s_add_u32 s42, s56, 0x20000
	s_addc_u32 s43, s57, 0
	s_mov_b32 m0, s59
	s_nop 0
	global_load_lds_dwordx4 v164, s[42:43]
	s_mov_b32 m0, s62
	s_nop 0
	global_load_lds_dwordx4 v162, s[42:43]
	ds_read_b128 v[72:75], v140
	ds_read_b128 v[76:79], v140 offset:1024
	ds_read_b128 v[136:139], v140 offset:2048
	ds_read_b128 v[140:143], v140 offset:3072
	ds_read_b128 v[144:147], v156
	ds_read_b128 v[148:151], v156 offset:1024
	ds_read_b128 v[152:155], v156 offset:2048
	ds_read_b128 v[156:159], v156 offset:3072
	ds_read_b128 v[170:173], v185 offset:32768
	ds_read_b128 v[174:177], v185 offset:33792
	ds_read_b128 v[178:181], v185 offset:34816
	ds_read_b128 v[186:189], v185 offset:35840
	ds_read_b128 v[194:197], v185 offset:36864
	ds_read_b128 v[198:201], v185 offset:37888
	ds_read_b128 v[202:205], v185 offset:38912
	ds_read_b128 v[212:215], v185 offset:39936
	s_waitcnt vmcnt(8)
	s_waitcnt lgkmcnt(0)
	s_barrier
	s_setprio 1
	s_waitcnt lgkmcnt(0)
	v_mfma_f32_16x16x32_bf16 v[64:67], v[72:75], v[170:173], v[64:67]
	v_mfma_f32_16x16x32_bf16 v[60:63], v[136:139], v[170:173], v[60:63]
	v_mfma_f32_16x16x32_bf16 v[124:127], v[72:75], v[178:181], v[124:127]
	v_mfma_f32_16x16x32_bf16 v[120:123], v[136:139], v[178:181], v[120:123]
	v_mfma_f32_16x16x32_bf16 v[108:111], v[72:75], v[194:197], v[108:111]
	v_mfma_f32_16x16x32_bf16 v[104:107], v[136:139], v[194:197], v[104:107]
	v_mfma_f32_16x16x32_bf16 v[92:95], v[72:75], v[202:205], v[92:95]
	v_mfma_f32_16x16x32_bf16 v[88:91], v[136:139], v[202:205], v[88:91]
	v_mfma_f32_16x16x32_bf16 v[64:67], v[76:79], v[174:177], v[64:67]
	v_mfma_f32_16x16x32_bf16 v[60:63], v[140:143], v[174:177], v[60:63]
	v_mfma_f32_16x16x32_bf16 v[124:127], v[76:79], v[186:189], v[124:127]
	v_mfma_f32_16x16x32_bf16 v[120:123], v[140:143], v[186:189], v[120:123]
	v_mfma_f32_16x16x32_bf16 v[108:111], v[76:79], v[198:201], v[108:111]
	v_mfma_f32_16x16x32_bf16 v[104:107], v[140:143], v[198:201], v[104:107]
	v_mfma_f32_16x16x32_bf16 v[92:95], v[76:79], v[212:215], v[92:95]
	v_mfma_f32_16x16x32_bf16 v[88:91], v[140:143], v[212:215], v[88:91]
	s_setprio 0
	s_setprio 1
	v_mfma_f32_16x16x32_bf16 v[132:135], v[144:147], v[170:173], v[132:135]
	v_mfma_f32_16x16x32_bf16 v[128:131], v[152:155], v[170:173], v[128:131]
	v_mfma_f32_16x16x32_bf16 v[116:119], v[144:147], v[178:181], v[116:119]
	v_mfma_f32_16x16x32_bf16 v[112:115], v[152:155], v[178:181], v[112:115]
	v_mfma_f32_16x16x32_bf16 v[100:103], v[144:147], v[194:197], v[100:103]
	v_mfma_f32_16x16x32_bf16 v[96:99], v[152:155], v[194:197], v[96:99]
	v_mfma_f32_16x16x32_bf16 v[84:87], v[144:147], v[202:205], v[84:87]
	v_mfma_f32_16x16x32_bf16 v[80:83], v[152:155], v[202:205], v[80:83]
	v_mfma_f32_16x16x32_bf16 v[132:135], v[148:151], v[174:177], v[132:135]
	v_mfma_f32_16x16x32_bf16 v[128:131], v[156:159], v[174:177], v[128:131]
	v_mfma_f32_16x16x32_bf16 v[116:119], v[148:151], v[186:189], v[116:119]
	v_mfma_f32_16x16x32_bf16 v[112:115], v[156:159], v[186:189], v[112:115]
	v_mfma_f32_16x16x32_bf16 v[100:103], v[148:151], v[198:201], v[100:103]
	v_mfma_f32_16x16x32_bf16 v[96:99], v[156:159], v[198:201], v[96:99]
	v_mfma_f32_16x16x32_bf16 v[84:87], v[148:151], v[212:215], v[84:87]
	v_mfma_f32_16x16x32_bf16 v[80:83], v[156:159], v[212:215], v[80:83]
	s_setprio 0
	s_barrier
	s_add_i32 s8, s8, s52
	s_mov_b32 m0, s66
	s_add_u32 s100, s56, 0x80
	s_addc_u32 s101, s57, 0
	global_load_lds_dwordx4 v164, s[100:101]
	s_mov_b32 m0, s67
	s_nop 0
	global_load_lds_dwordx4 v162, s[100:101]
	s_mov_b32 m0, s8
	ds_read_b128 v[170:173], v185 offset:49152
	ds_read_b128 v[174:177], v185 offset:50176
	ds_read_b128 v[178:181], v185 offset:51200
	ds_read_b128 v[186:189], v185 offset:52224
	ds_read_b128 v[194:197], v185 offset:53248
	ds_read_b128 v[198:201], v185 offset:54272
	ds_read_b128 v[202:205], v185 offset:55296
	ds_read_b128 v[212:215], v185 offset:56320
	s_add_u32 s100, s54, 0x80
	s_addc_u32 s101, s55, 0
	global_load_lds_dwordx4 v192, s[100:101]
	s_add_i32 m0, s8, 0x2000
	s_add_u32 s42, s54, 0x20080
	s_addc_u32 s43, s55, 0
	s_add_i32 s8, s9, s52
	global_load_lds_dwordx4 v160, s[100:101]
	s_mov_b32 m0, s8
	s_nop 0
	global_load_lds_dwordx4 v192, s[42:43]
	s_add_i32 m0, s8, 0x2000
	s_nop 0
	global_load_lds_dwordx4 v160, s[42:43]
	s_waitcnt vmcnt(8)
	s_waitcnt lgkmcnt(0)
	s_barrier
	s_setprio 1
	s_waitcnt lgkmcnt(0)
	v_mfma_f32_16x16x32_bf16 v[68:71], v[72:75], v[170:173], v[68:71]
	v_mfma_f32_16x16x32_bf16 v[56:59], v[136:139], v[170:173], v[56:59]
	v_mfma_f32_16x16x32_bf16 v[44:47], v[72:75], v[178:181], v[44:47]
	v_mfma_f32_16x16x32_bf16 v[40:43], v[136:139], v[178:181], v[40:43]
	v_mfma_f32_16x16x32_bf16 v[28:31], v[72:75], v[194:197], v[28:31]
	v_mfma_f32_16x16x32_bf16 v[24:27], v[136:139], v[194:197], v[24:27]
	v_mfma_f32_16x16x32_bf16 v[12:15], v[72:75], v[202:205], v[12:15]
	v_mfma_f32_16x16x32_bf16 v[8:11], v[136:139], v[202:205], v[8:11]
	v_mfma_f32_16x16x32_bf16 v[68:71], v[76:79], v[174:177], v[68:71]
	v_mfma_f32_16x16x32_bf16 v[56:59], v[140:143], v[174:177], v[56:59]
	v_mfma_f32_16x16x32_bf16 v[44:47], v[76:79], v[186:189], v[44:47]
	v_mfma_f32_16x16x32_bf16 v[40:43], v[140:143], v[186:189], v[40:43]
	v_mfma_f32_16x16x32_bf16 v[28:31], v[76:79], v[198:201], v[28:31]
	v_mfma_f32_16x16x32_bf16 v[24:27], v[140:143], v[198:201], v[24:27]
	v_mfma_f32_16x16x32_bf16 v[12:15], v[76:79], v[212:215], v[12:15]
	v_mfma_f32_16x16x32_bf16 v[8:11], v[140:143], v[212:215], v[8:11]
	s_setprio 0
	s_setprio 1
	v_mfma_f32_16x16x32_bf16 v[52:55], v[144:147], v[170:173], v[52:55]
	v_mfma_f32_16x16x32_bf16 v[48:51], v[152:155], v[170:173], v[48:51]
	v_mfma_f32_16x16x32_bf16 v[36:39], v[144:147], v[178:181], v[36:39]
	v_mfma_f32_16x16x32_bf16 v[32:35], v[152:155], v[178:181], v[32:35]
	v_mfma_f32_16x16x32_bf16 v[20:23], v[144:147], v[194:197], v[20:23]
	v_mfma_f32_16x16x32_bf16 v[16:19], v[152:155], v[194:197], v[16:19]
	v_mfma_f32_16x16x32_bf16 v[4:7], v[144:147], v[202:205], v[4:7]
	v_mfma_f32_16x16x32_bf16 v[0:3], v[152:155], v[202:205], v[0:3]
	v_mfma_f32_16x16x32_bf16 v[52:55], v[148:151], v[174:177], v[52:55]
	v_mfma_f32_16x16x32_bf16 v[48:51], v[156:159], v[174:177], v[48:51]
	v_mfma_f32_16x16x32_bf16 v[36:39], v[148:151], v[186:189], v[36:39]
	v_mfma_f32_16x16x32_bf16 v[32:35], v[156:159], v[186:189], v[32:35]
	v_mfma_f32_16x16x32_bf16 v[20:23], v[148:151], v[198:201], v[20:23]
	v_mfma_f32_16x16x32_bf16 v[16:19], v[156:159], v[198:201], v[16:19]
	v_mfma_f32_16x16x32_bf16 v[4:7], v[148:151], v[212:215], v[4:7]
	v_mfma_f32_16x16x32_bf16 v[0:3], v[156:159], v[212:215], v[0:3]
	s_setprio 0
	s_barrier
	s_add_i32 vcc_lo, vcc_lo, 2
	s_add_u32 s44, s44, 0x100
	s_addc_u32 s45, s45, 0
	s_add_u32 s91, s91, 0x100
	s_addc_u32 s92, s92, 0
	s_cmp_gt_u32 vcc_lo, 5
	s_cbranch_scc0 .LBB0_388
	s_and_b64 vcc, exec, s[40:41]
	s_cbranch_vccz .LBB0_391
	s_barrier

; #define PG8_STAGE(bufoff, gbase, voff) do { _Pragma("unroll") for (int _i = 0; _i < 2; ++_i) \
;         __builtin_amdgcn_global_load_lds((const unsigned*)((const char*)(gbase) + (voff)[_i]), (LAS unsigned*)(lds + (bufoff) + ldsw + _i * 8192), 16, 0, 0); } while (0)
; #define PG8_LDA(dst, b, h) do { _Pragma("unroll") for (int m = 0; m < 4; ++m) _Pragma("unroll") for (int k = 0; k < 2; ++k) dst[m][k] = *(const LAS bf16x8*)(lds + PG8_SA(b, h) + aoff + m * 2048 + k * 1024); } while (0)
; #define PG8_LDB(dst, b, h) do { _Pragma("unroll") for (int n = 0; n < 2; ++n) _Pragma("unroll") for (int k = 0; k < 2; ++k) dst[n][k] = *(const LAS bf16x8*)(lds + PG8_SB(b, h) + boff + n * 2048 + k * 1024); } while (0)
; #define PG8_MMA(ai, bj, At, Bt) do { __builtin_amdgcn_s_setprio(1); _Pragma("unroll") for (int m = 0; m < 4; ++m) _Pragma("unroll") for (int n = 0; n < 2; ++n) _Pragma("unroll") for (int k = 0; k < 2; ++k) \
;         acc[ai][bj][m][n] = __builtin_amdgcn_mfma_f32_16x16x32_bf16(Bt[n][k], At[m][k], acc[ai][bj][m][n], 0, 0, 0); __builtin_amdgcn_s_setprio(0); } while (0)
; #define PG8_WAIT_V(n) asm volatile("s_waitcnt vmcnt(" #n ")" ::: "memory")
; #define PG8_WAIT_L(n) asm volatile("s_waitcnt lgkmcnt(" #n ")" ::: "memory")
; #define PG8_BAR __builtin_amdgcn_s_barrier()
; #define PG8_SCHED __builtin_amdgcn_sched_barrier(0)
; template <class Epi, class Sched, bool ALIGN_EPI>
; __device__ __forceinline__ void gemm_phase(LAS unsigned char* lds, const Gemm g, const Sched& S, const Epi& E) {
;     ...
;             PG8_LDB(B0, 0, 0); PG8_LDB(B1, 0, 1); PG8_SCHED; PG8_LDA(At, 0, 0); PG8_STAGE(PG8_SA(1, 1), a1 + hstepA, voffA);
;             PG8_WAIT_V(8); PG8_WAIT_L(0); PG8_BAR; PG8_MMA(0, 0, At, B0); PG8_MMA(0, 1, At, B1); PG8_BAR; PG8_SCHED;
;             PG8_LDA(At, 0, 1); PG8_STAGE(PG8_SB(0, 0), b2, voffB); PG8_STAGE(PG8_SB(0, 1), b2 + hstepB, voffB); PG8_STAGE(PG8_SA(0, 0), a2, voffA);
;             PG8_WAIT_V(8); PG8_WAIT_L(0); PG8_BAR; PG8_MMA(1, 0, At, B0); PG8_MMA(1, 1, At, B1); PG8_BAR; PG8_SCHED;
.LBB0_434:
	s_add_u32 s6, s4, 0x100
	s_addc_u32 s7, s5, 0
	s_add_i32 s77, 0, 0x10000
	s_cmp_eq_u32 s66, 8
	s_cselect_b32 s39, s45, s7
	s_cselect_b32 s38, s44, s6
	s_cselect_b32 s17, s21, s53
	s_cselect_b32 s16, s20, s52
	s_add_i32 s80, 0, 0x14000
	v_add_u32_e32 v156, s77, v142
	v_add_u32_e32 v172, s80, v142
	v_lshl_add_u64 v[216:217], s[4:5], 0, v[136:137]
	s_add_i32 m0, s57, 0xc000
	s_nop 0
	global_load_lds_dwordx4 v[216:217], off
	v_lshl_add_u64 v[216:217], s[4:5], 0, v[138:139]
	s_add_i32 m0, s57, 0xe000
	s_nop 0
	global_load_lds_dwordx4 v[216:217], off
	ds_read_b128 v[144:147], v156
	ds_read_b128 v[148:151], v156 offset:1024
	ds_read_b128 v[152:155], v156 offset:2048
	ds_read_b128 v[156:159], v156 offset:3072
	ds_read_b128 v[160:163], v172
	ds_read_b128 v[164:167], v172 offset:1024
	ds_read_b128 v[168:171], v172 offset:2048
	ds_read_b128 v[172:175], v172 offset:3072
	ds_read_b128 v[176:179], v143
	ds_read_b128 v[180:183], v143 offset:1024
	ds_read_b128 v[184:187], v143 offset:2048
	ds_read_b128 v[188:191], v143 offset:3072
	ds_read_b128 v[194:197], v143 offset:4096
	ds_read_b128 v[198:201], v143 offset:5120
	ds_read_b128 v[202:205], v143 offset:6144
	ds_read_b128 v[212:215], v143 offset:7168
	s_waitcnt vmcnt(8)
	s_waitcnt lgkmcnt(0)
	s_barrier
	s_setprio 1
	s_waitcnt lgkmcnt(0)
	v_mfma_f32_16x16x32_bf16 v[124:127], v[144:147], v[176:179], v[124:127]
	v_mfma_f32_16x16x32_bf16 v[120:123], v[152:155], v[176:179], v[120:123]
	v_mfma_f32_16x16x32_bf16 v[108:111], v[144:147], v[184:187], v[108:111]
	v_mfma_f32_16x16x32_bf16 v[104:107], v[152:155], v[184:187], v[104:107]
	v_mfma_f32_16x16x32_bf16 v[92:95], v[144:147], v[194:197], v[92:95]
	v_mfma_f32_16x16x32_bf16 v[88:91], v[152:155], v[194:197], v[88:91]
	v_mfma_f32_16x16x32_bf16 v[76:79], v[144:147], v[202:205], v[76:79]
	v_mfma_f32_16x16x32_bf16 v[72:75], v[152:155], v[202:205], v[72:75]
	v_mfma_f32_16x16x32_bf16 v[124:127], v[148:151], v[180:183], v[124:127]
	v_mfma_f32_16x16x32_bf16 v[120:123], v[156:159], v[180:183], v[120:123]
	v_mfma_f32_16x16x32_bf16 v[108:111], v[148:151], v[188:191], v[108:111]
	v_mfma_f32_16x16x32_bf16 v[104:107], v[156:159], v[188:191], v[104:107]
	v_mfma_f32_16x16x32_bf16 v[92:95], v[148:151], v[198:201], v[92:95]
	v_mfma_f32_16x16x32_bf16 v[88:91], v[156:159], v[198:201], v[88:91]
	v_mfma_f32_16x16x32_bf16 v[76:79], v[148:151], v[212:215], v[76:79]
	v_mfma_f32_16x16x32_bf16 v[72:75], v[156:159], v[212:215], v[72:75]
	s_setprio 0
	s_setprio 1
	v_mfma_f32_16x16x32_bf16 v[116:119], v[160:163], v[176:179], v[116:119]
	v_mfma_f32_16x16x32_bf16 v[112:115], v[168:171], v[176:179], v[112:115]
	v_mfma_f32_16x16x32_bf16 v[100:103], v[160:163], v[184:187], v[100:103]
	v_mfma_f32_16x16x32_bf16 v[96:99], v[168:171], v[184:187], v[96:99]
	v_mfma_f32_16x16x32_bf16 v[84:87], v[160:163], v[194:197], v[84:87]
	v_mfma_f32_16x16x32_bf16 v[80:83], v[168:171], v[194:197], v[80:83]
	v_mfma_f32_16x16x32_bf16 v[68:71], v[160:163], v[202:205], v[68:71]
	v_mfma_f32_16x16x32_bf16 v[64:67], v[168:171], v[202:205], v[64:67]
	v_mfma_f32_16x16x32_bf16 v[116:119], v[164:167], v[180:183], v[116:119]
	v_mfma_f32_16x16x32_bf16 v[112:115], v[172:175], v[180:183], v[112:115]
	v_mfma_f32_16x16x32_bf16 v[100:103], v[164:167], v[188:191], v[100:103]
	v_mfma_f32_16x16x32_bf16 v[96:99], v[172:175], v[188:191], v[96:99]
	v_mfma_f32_16x16x32_bf16 v[84:87], v[164:167], v[198:201], v[84:87]
	v_mfma_f32_16x16x32_bf16 v[80:83], v[172:175], v[198:201], v[80:83]
	v_mfma_f32_16x16x32_bf16 v[68:71], v[164:167], v[212:215], v[68:71]
	v_mfma_f32_16x16x32_bf16 v[64:67], v[172:175], v[212:215], v[64:67]
	s_setprio 0
	s_barrier
	s_add_i32 s4, s77, s56
	s_mov_b32 m0, s57
	s_nop 0
	global_load_lds_dwordx4 v134, s[38:39]
	s_mov_b32 m0, s58
	s_nop 0
	global_load_lds_dwordx4 v130, s[38:39]
	s_mov_b32 m0, s4
	ds_read_b128 v[176:179], v143 offset:16384
	ds_read_b128 v[180:183], v143 offset:17408
	ds_read_b128 v[184:187], v143 offset:18432
	ds_read_b128 v[188:191], v143 offset:19456
	ds_read_b128 v[194:197], v143 offset:20480
	ds_read_b128 v[198:201], v143 offset:21504
	ds_read_b128 v[202:205], v143 offset:22528
	ds_read_b128 v[212:215], v143 offset:23552
	global_load_lds_dwordx4 v132, s[16:17]
	s_add_i32 m0, s4, 0x2000
	s_add_u32 s4, s16, 0x30000
	v_lshl_add_u64 v[218:219], s[16:17], 0, v[128:129]
	s_addc_u32 s5, s17, 0
	s_add_i32 s77, s80, s56
	global_load_lds_dwordx4 v128, s[16:17]
	s_mov_b32 m0, s77
	s_nop 0
	global_load_lds_dwordx4 v132, s[4:5]
	s_add_i32 m0, s77, 0x2000
	s_nop 0
	global_load_lds_dwordx4 v128, s[4:5]
	s_waitcnt vmcnt(8)
	s_waitcnt lgkmcnt(0)
	s_barrier
; #define PG8_STAGE(bufoff, gbase, voff) do { _Pragma("unroll") for (int _i = 0; _i < 2; ++_i) \
;         __builtin_amdgcn_global_load_lds((const unsigned*)((const char*)(gbase) + (voff)[_i]), (LAS unsigned*)(lds + (bufoff) + ldsw + _i * 8192), 16, 0, 0); } while (0)
; #define PG8_LDA(dst, b, h) do { _Pragma("unroll") for (int m = 0; m < 4; ++m) _Pragma("unroll") for (int k = 0; k < 2; ++k) dst[m][k] = *(const LAS bf16x8*)(lds + PG8_SA(b, h) + aoff + m * 2048 + k * 1024); } while (0)
; #define PG8_LDB(dst, b, h) do { _Pragma("unroll") for (int n = 0; n < 2; ++n) _Pragma("unroll") for (int k = 0; k < 2; ++k) dst[n][k] = *(const LAS bf16x8*)(lds + PG8_SB(b, h) + boff + n * 2048 + k * 1024); } while (0)
; #define PG8_MMA(ai, bj, At, Bt) do { __builtin_amdgcn_s_setprio(1); _Pragma("unroll") for (int m = 0; m < 4; ++m) _Pragma("unroll") for (int n = 0; n < 2; ++n) _Pragma("unroll") for (int k = 0; k < 2; ++k) \
;         acc[ai][bj][m][n] = __builtin_amdgcn_mfma_f32_16x16x32_bf16(Bt[n][k], At[m][k], acc[ai][bj][m][n], 0, 0, 0); __builtin_amdgcn_s_setprio(0); } while (0)
; #define PG8_WAIT_V(n) asm volatile("s_waitcnt vmcnt(" #n ")" ::: "memory")
; #define PG8_WAIT_L(n) asm volatile("s_waitcnt lgkmcnt(" #n ")" ::: "memory")
; #define PG8_BAR __builtin_amdgcn_s_barrier()
; #define PG8_SCHED __builtin_amdgcn_sched_barrier(0)
; template <class Epi, class Sched, bool ALIGN_EPI>
; __device__ __forceinline__ void gemm_phase(LAS unsigned char* lds, const Gemm g, const Sched& S, const Epi& E) {
;     ...
;             PG8_WAIT_V(8); PG8_WAIT_L(0); PG8_BAR; PG8_MMA(1, 0, At, B0); PG8_MMA(1, 1, At, B1); PG8_BAR; PG8_SCHED;
;             PG8_LDB(B0, 1, 0); PG8_LDB(B1, 1, 1); PG8_SCHED; PG8_LDA(At, 1, 0); PG8_STAGE(PG8_SA(0, 1), a2 + hstepA, voffA);
;             PG8_WAIT_V(8); PG8_WAIT_L(0); PG8_BAR; PG8_MMA(0, 0, At, B0); PG8_MMA(0, 1, At, B1); PG8_BAR; PG8_SCHED;
	s_setprio 1
	s_waitcnt lgkmcnt(0)
	v_mfma_f32_16x16x32_bf16 v[60:63], v[144:147], v[176:179], v[60:63]
	v_mfma_f32_16x16x32_bf16 v[56:59], v[152:155], v[176:179], v[56:59]
	v_mfma_f32_16x16x32_bf16 v[44:47], v[144:147], v[184:187], v[44:47]
	v_mfma_f32_16x16x32_bf16 v[40:43], v[152:155], v[184:187], v[40:43]
	v_mfma_f32_16x16x32_bf16 v[28:31], v[144:147], v[194:197], v[28:31]
	v_mfma_f32_16x16x32_bf16 v[24:27], v[152:155], v[194:197], v[24:27]
	v_mfma_f32_16x16x32_bf16 v[12:15], v[144:147], v[202:205], v[12:15]
	v_mfma_f32_16x16x32_bf16 v[8:11], v[152:155], v[202:205], v[8:11]
	v_mfma_f32_16x16x32_bf16 v[60:63], v[148:151], v[180:183], v[60:63]
	v_mfma_f32_16x16x32_bf16 v[56:59], v[156:159], v[180:183], v[56:59]
	v_mfma_f32_16x16x32_bf16 v[44:47], v[148:151], v[188:191], v[44:47]
	v_mfma_f32_16x16x32_bf16 v[40:43], v[156:159], v[188:191], v[40:43]
	v_mfma_f32_16x16x32_bf16 v[28:31], v[148:151], v[198:201], v[28:31]
	v_mfma_f32_16x16x32_bf16 v[24:27], v[156:159], v[198:201], v[24:27]
	v_mfma_f32_16x16x32_bf16 v[12:15], v[148:151], v[212:215], v[12:15]
	v_mfma_f32_16x16x32_bf16 v[8:11], v[156:159], v[212:215], v[8:11]
	s_setprio 0
	s_setprio 1
	v_mfma_f32_16x16x32_bf16 v[52:55], v[160:163], v[176:179], v[52:55]
	v_mfma_f32_16x16x32_bf16 v[48:51], v[168:171], v[176:179], v[48:51]
	v_mfma_f32_16x16x32_bf16 v[36:39], v[160:163], v[184:187], v[36:39]
	v_mfma_f32_16x16x32_bf16 v[32:35], v[168:171], v[184:187], v[32:35]
	v_mfma_f32_16x16x32_bf16 v[20:23], v[160:163], v[194:197], v[20:23]
	v_mfma_f32_16x16x32_bf16 v[16:19], v[168:171], v[194:197], v[16:19]
	v_mfma_f32_16x16x32_bf16 v[4:7], v[160:163], v[202:205], v[4:7]
	v_mfma_f32_16x16x32_bf16 v[0:3], v[168:171], v[202:205], v[0:3]
	v_mfma_f32_16x16x32_bf16 v[52:55], v[164:167], v[180:183], v[52:55]
	v_mfma_f32_16x16x32_bf16 v[48:51], v[172:175], v[180:183], v[48:51]
	v_mfma_f32_16x16x32_bf16 v[36:39], v[164:167], v[188:191], v[36:39]
	v_mfma_f32_16x16x32_bf16 v[32:35], v[172:175], v[188:191], v[32:35]
	v_mfma_f32_16x16x32_bf16 v[20:23], v[164:167], v[198:201], v[20:23]
	v_mfma_f32_16x16x32_bf16 v[16:19], v[172:175], v[198:201], v[16:19]
	v_mfma_f32_16x16x32_bf16 v[4:7], v[164:167], v[212:215], v[4:7]
	v_mfma_f32_16x16x32_bf16 v[0:3], v[172:175], v[212:215], v[0:3]
	s_setprio 0
	s_barrier
	s_add_i32 s77, 0, 0x18000
	s_add_i32 s80, 0, 0x1c000
	v_add_u32_e32 v156, s77, v142
	v_add_u32_e32 v172, s80, v142
	s_add_u32 s4, s38, 0x30000
	s_addc_u32 s5, s39, 0
	s_mov_b32 m0, s59
	s_nop 0
	global_load_lds_dwordx4 v134, s[4:5]
	s_mov_b32 m0, s62
	s_nop 0
	global_load_lds_dwordx4 v130, s[4:5]
	ds_read_b128 v[144:147], v156
	ds_read_b128 v[148:151], v156 offset:1024
	ds_read_b128 v[152:155], v156 offset:2048
	ds_read_b128 v[156:159], v156 offset:3072
	ds_read_b128 v[160:163], v172
	ds_read_b128 v[164:167], v172 offset:1024
	ds_read_b128 v[168:171], v172 offset:2048
	ds_read_b128 v[172:175], v172 offset:3072
	ds_read_b128 v[176:179], v143 offset:32768
	ds_read_b128 v[180:183], v143 offset:33792
	ds_read_b128 v[184:187], v143 offset:34816
	ds_read_b128 v[188:191], v143 offset:35840
	ds_read_b128 v[194:197], v143 offset:36864
	ds_read_b128 v[198:201], v143 offset:37888
	ds_read_b128 v[202:205], v143 offset:38912
	ds_read_b128 v[212:215], v143 offset:39936
	s_waitcnt vmcnt(8)
	s_waitcnt lgkmcnt(0)
	s_barrier
	s_setprio 1
	s_waitcnt lgkmcnt(0)
	v_mfma_f32_16x16x32_bf16 v[124:127], v[144:147], v[176:179], v[124:127]
	v_mfma_f32_16x16x32_bf16 v[120:123], v[152:155], v[176:179], v[120:123]
	v_mfma_f32_16x16x32_bf16 v[108:111], v[144:147], v[184:187], v[108:111]
	v_mfma_f32_16x16x32_bf16 v[104:107], v[152:155], v[184:187], v[104:107]
	v_mfma_f32_16x16x32_bf16 v[92:95], v[144:147], v[194:197], v[92:95]
	v_mfma_f32_16x16x32_bf16 v[88:91], v[152:155], v[194:197], v[88:91]
	v_mfma_f32_16x16x32_bf16 v[76:79], v[144:147], v[202:205], v[76:79]
	v_mfma_f32_16x16x32_bf16 v[72:75], v[152:155], v[202:205], v[72:75]
	v_mfma_f32_16x16x32_bf16 v[124:127], v[148:151], v[180:183], v[124:127]
	v_mfma_f32_16x16x32_bf16 v[120:123], v[156:159], v[180:183], v[120:123]
	v_mfma_f32_16x16x32_bf16 v[108:111], v[148:151], v[188:191], v[108:111]
	v_mfma_f32_16x16x32_bf16 v[104:107], v[156:159], v[188:191], v[104:107]
	v_mfma_f32_16x16x32_bf16 v[92:95], v[148:151], v[198:201], v[92:95]
	v_mfma_f32_16x16x32_bf16 v[88:91], v[156:159], v[198:201], v[88:91]
	v_mfma_f32_16x16x32_bf16 v[76:79], v[148:151], v[212:215], v[76:79]
	v_mfma_f32_16x16x32_bf16 v[72:75], v[156:159], v[212:215], v[72:75]
	s_setprio 0
	s_setprio 1
	v_mfma_f32_16x16x32_bf16 v[116:119], v[160:163], v[176:179], v[116:119]
	v_mfma_f32_16x16x32_bf16 v[112:115], v[168:171], v[176:179], v[112:115]
	v_mfma_f32_16x16x32_bf16 v[100:103], v[160:163], v[184:187], v[100:103]
	v_mfma_f32_16x16x32_bf16 v[96:99], v[168:171], v[184:187], v[96:99]
	v_mfma_f32_16x16x32_bf16 v[84:87], v[160:163], v[194:197], v[84:87]
	v_mfma_f32_16x16x32_bf16 v[80:83], v[168:171], v[194:197], v[80:83]
	v_mfma_f32_16x16x32_bf16 v[68:71], v[160:163], v[202:205], v[68:71]
	v_mfma_f32_16x16x32_bf16 v[64:67], v[168:171], v[202:205], v[64:67]
	v_mfma_f32_16x16x32_bf16 v[116:119], v[164:167], v[180:183], v[116:119]
	v_mfma_f32_16x16x32_bf16 v[112:115], v[172:175], v[180:183], v[112:115]
	v_mfma_f32_16x16x32_bf16 v[100:103], v[164:167], v[188:191], v[100:103]
	v_mfma_f32_16x16x32_bf16 v[96:99], v[172:175], v[188:191], v[96:99]
	v_mfma_f32_16x16x32_bf16 v[84:87], v[164:167], v[198:201], v[84:87]
	v_mfma_f32_16x16x32_bf16 v[80:83], v[172:175], v[198:201], v[80:83]
	v_mfma_f32_16x16x32_bf16 v[68:71], v[164:167], v[212:215], v[68:71]
	v_mfma_f32_16x16x32_bf16 v[64:67], v[172:175], v[212:215], v[64:67]
	s_setprio 0
	s_barrier
; #define PG8_STAGE(bufoff, gbase, voff) do { _Pragma("unroll") for (int _i = 0; _i < 2; ++_i) \
;         __builtin_amdgcn_global_load_lds((const unsigned*)((const char*)(gbase) + (voff)[_i]), (LAS unsigned*)(lds + (bufoff) + ldsw + _i * 8192), 16, 0, 0); } while (0)
; #define PG8_LDA(dst, b, h) do { _Pragma("unroll") for (int m = 0; m < 4; ++m) _Pragma("unroll") for (int k = 0; k < 2; ++k) dst[m][k] = *(const LAS bf16x8*)(lds + PG8_SA(b, h) + aoff + m * 2048 + k * 1024); } while (0)
; #define PG8_MMA(ai, bj, At, Bt) do { __builtin_amdgcn_s_setprio(1); _Pragma("unroll") for (int m = 0; m < 4; ++m) _Pragma("unroll") for (int n = 0; n < 2; ++n) _Pragma("unroll") for (int k = 0; k < 2; ++k) \
;         acc[ai][bj][m][n] = __builtin_amdgcn_mfma_f32_16x16x32_bf16(Bt[n][k], At[m][k], acc[ai][bj][m][n], 0, 0, 0); __builtin_amdgcn_s_setprio(0); } while (0)
; #define PG8_WAIT_V(n) asm volatile("s_waitcnt vmcnt(" #n ")" ::: "memory")
; #define PG8_WAIT_L(n) asm volatile("s_waitcnt lgkmcnt(" #n ")" ::: "memory")
; #define PG8_BAR __builtin_amdgcn_s_barrier()
; #define PG8_SCHED __builtin_amdgcn_sched_barrier(0)
; template <class Epi, class Sched, bool ALIGN_EPI>
; __device__ __forceinline__ void gemm_phase(LAS unsigned char* lds, const Gemm g, const Sched& S, const Epi& E) {
;     ...
;             PG8_LDA(At, 1, 1); PG8_STAGE(PG8_SB(1, 0), b3, voffB); PG8_STAGE(PG8_SB(1, 1), b3 + hstepB, voffB); PG8_STAGE(PG8_SA(1, 0), a3, voffA);
;             PG8_WAIT_V(8); PG8_WAIT_L(0); PG8_BAR; PG8_MMA(1, 0, At, B0); PG8_MMA(1, 1, At, B1); PG8_BAR; PG8_SCHED;
;         }
	s_add_i32 s4, s77, s56
	s_mov_b32 m0, s65
	s_add_u32 s100, s38, 0x80
	s_addc_u32 s101, s39, 0
	global_load_lds_dwordx4 v134, s[100:101]
	s_mov_b32 m0, s67
	s_nop 0
	global_load_lds_dwordx4 v130, s[100:101]
	s_mov_b32 m0, s4
	ds_read_b128 v[176:179], v143 offset:49152
	ds_read_b128 v[180:183], v143 offset:50176
	ds_read_b128 v[184:187], v143 offset:51200
	ds_read_b128 v[188:191], v143 offset:52224
	ds_read_b128 v[194:197], v143 offset:53248
	ds_read_b128 v[198:201], v143 offset:54272
	ds_read_b128 v[202:205], v143 offset:55296
	ds_read_b128 v[212:215], v143 offset:56320
	s_add_u32 s100, s16, 0x80
	s_addc_u32 s101, s17, 0
	global_load_lds_dwordx4 v132, s[100:101]
	s_add_i32 m0, s4, 0x2000
	s_add_u32 s4, s16, 0x30080
	v_lshl_add_u64 v[216:217], v[218:219], 0, s[12:13]
	s_addc_u32 s5, s17, 0
	s_add_i32 s16, s80, s56
	global_load_lds_dwordx4 v[216:217], off
	s_mov_b32 m0, s16
	s_nop 0
	global_load_lds_dwordx4 v132, s[4:5]
	s_add_i32 m0, s16, 0x2000
	s_nop 0
	global_load_lds_dwordx4 v128, s[4:5]
	s_waitcnt vmcnt(8)
	s_waitcnt lgkmcnt(0)
	s_barrier
	s_setprio 1
	s_waitcnt lgkmcnt(0)
	v_mfma_f32_16x16x32_bf16 v[60:63], v[144:147], v[176:179], v[60:63]
	v_mfma_f32_16x16x32_bf16 v[56:59], v[152:155], v[176:179], v[56:59]
	v_mfma_f32_16x16x32_bf16 v[44:47], v[144:147], v[184:187], v[44:47]
	v_mfma_f32_16x16x32_bf16 v[40:43], v[152:155], v[184:187], v[40:43]
	v_mfma_f32_16x16x32_bf16 v[28:31], v[144:147], v[194:197], v[28:31]
	v_mfma_f32_16x16x32_bf16 v[24:27], v[152:155], v[194:197], v[24:27]
	v_mfma_f32_16x16x32_bf16 v[12:15], v[144:147], v[202:205], v[12:15]
	v_mfma_f32_16x16x32_bf16 v[8:11], v[152:155], v[202:205], v[8:11]
	v_mfma_f32_16x16x32_bf16 v[60:63], v[148:151], v[180:183], v[60:63]
	v_mfma_f32_16x16x32_bf16 v[56:59], v[156:159], v[180:183], v[56:59]
	v_mfma_f32_16x16x32_bf16 v[44:47], v[148:151], v[188:191], v[44:47]
	v_mfma_f32_16x16x32_bf16 v[40:43], v[156:159], v[188:191], v[40:43]
	v_mfma_f32_16x16x32_bf16 v[28:31], v[148:151], v[198:201], v[28:31]
	v_mfma_f32_16x16x32_bf16 v[24:27], v[156:159], v[198:201], v[24:27]
	v_mfma_f32_16x16x32_bf16 v[12:15], v[148:151], v[212:215], v[12:15]
	v_mfma_f32_16x16x32_bf16 v[8:11], v[156:159], v[212:215], v[8:11]
	s_setprio 0
	s_setprio 1
	v_mfma_f32_16x16x32_bf16 v[52:55], v[160:163], v[176:179], v[52:55]
	v_mfma_f32_16x16x32_bf16 v[48:51], v[168:171], v[176:179], v[48:51]
	v_mfma_f32_16x16x32_bf16 v[36:39], v[160:163], v[184:187], v[36:39]
	v_mfma_f32_16x16x32_bf16 v[32:35], v[168:171], v[184:187], v[32:35]
	v_mfma_f32_16x16x32_bf16 v[20:23], v[160:163], v[194:197], v[20:23]
	v_mfma_f32_16x16x32_bf16 v[16:19], v[168:171], v[194:197], v[16:19]
	v_mfma_f32_16x16x32_bf16 v[4:7], v[160:163], v[202:205], v[4:7]
	v_mfma_f32_16x16x32_bf16 v[0:3], v[168:171], v[202:205], v[0:3]
	v_mfma_f32_16x16x32_bf16 v[52:55], v[164:167], v[180:183], v[52:55]
	v_mfma_f32_16x16x32_bf16 v[48:51], v[172:175], v[180:183], v[48:51]
	v_mfma_f32_16x16x32_bf16 v[36:39], v[164:167], v[188:191], v[36:39]
	v_mfma_f32_16x16x32_bf16 v[32:35], v[172:175], v[188:191], v[32:35]
	v_mfma_f32_16x16x32_bf16 v[20:23], v[164:167], v[198:201], v[20:23]
	v_mfma_f32_16x16x32_bf16 v[16:19], v[172:175], v[198:201], v[16:19]
	v_mfma_f32_16x16x32_bf16 v[4:7], v[164:167], v[212:215], v[4:7]
	v_mfma_f32_16x16x32_bf16 v[0:3], v[172:175], v[212:215], v[0:3]
	s_setprio 0
	s_barrier
	s_add_i32 s66, s66, 2
	s_add_u32 s52, s52, 0x100
	s_addc_u32 s53, s53, 0
	s_cmp_gt_u32 s66, 9
	s_mov_b64 s[4:5], s[6:7]
	s_cbranch_scc0 .LBB0_434
	s_and_b64 vcc, exec, s[8:9]
	s_cbranch_vccz .LBB0_437
	s_barrier

; #define PG8_STAGE(bufoff, gbase, voff) do { _Pragma("unroll") for (int _i = 0; _i < 2; ++_i) \
;         __builtin_amdgcn_global_load_lds((const unsigned*)((const char*)(gbase) + (voff)[_i]), (LAS unsigned*)(lds + (bufoff) + ldsw + _i * 8192), 16, 0, 0); } while (0)
; #define PG8_LDA(dst, b, h) do { _Pragma("unroll") for (int m = 0; m < 4; ++m) _Pragma("unroll") for (int k = 0; k < 2; ++k) dst[m][k] = *(const LAS bf16x8*)(lds + PG8_SA(b, h) + aoff + m * 2048 + k * 1024); } while (0)
; #define PG8_LDB(dst, b, h) do { _Pragma("unroll") for (int n = 0; n < 2; ++n) _Pragma("unroll") for (int k = 0; k < 2; ++k) dst[n][k] = *(const LAS bf16x8*)(lds + PG8_SB(b, h) + boff + n * 2048 + k * 1024); } while (0)
; #define PG8_MMA(ai, bj, At, Bt) do { __builtin_amdgcn_s_setprio(1); _Pragma("unroll") for (int m = 0; m < 4; ++m) _Pragma("unroll") for (int n = 0; n < 2; ++n) _Pragma("unroll") for (int k = 0; k < 2; ++k) \
;         acc[ai][bj][m][n] = __builtin_amdgcn_mfma_f32_16x16x32_bf16(Bt[n][k], At[m][k], acc[ai][bj][m][n], 0, 0, 0); __builtin_amdgcn_s_setprio(0); } while (0)
; #define PG8_WAIT_V(n) asm volatile("s_waitcnt vmcnt(" #n ")" ::: "memory")
; #define PG8_WAIT_L(n) asm volatile("s_waitcnt lgkmcnt(" #n ")" ::: "memory")
; #define PG8_BAR __builtin_amdgcn_s_barrier()
; #define PG8_SCHED __builtin_amdgcn_sched_barrier(0)
; template <class Epi, class Sched, bool ALIGN_EPI>
; __device__ __forceinline__ void gemm_phase(LAS unsigned char* lds, const Gemm g, const Sched& S, const Epi& E) {
;     ...
;             const char* a1 = cA + (size_t)(t + 1) * kstep;
;             const char* a2 = last ? nA : cA + (size_t)(t + 2) * kstep; const char* b2 = last ? nB : cB + (size_t)(t + 2) * kstep;
;             const char* a3 = a2 + kstep; const char* b3 = b2 + kstep;
;             PG8_LDB(B0, 0, 0); PG8_LDB(B1, 0, 1); PG8_SCHED; PG8_LDA(At, 0, 0); PG8_STAGE(PG8_SA(1, 1), a1 + hstepA, voffA);
;             PG8_WAIT_V(8); PG8_WAIT_L(0); PG8_BAR; PG8_MMA(0, 0, At, B0); PG8_MMA(0, 1, At, B1); PG8_BAR; PG8_SCHED;
;             PG8_LDA(At, 0, 1); PG8_STAGE(PG8_SB(0, 0), b2, voffB); PG8_STAGE(PG8_SB(0, 1), b2 + hstepB, voffB); PG8_STAGE(PG8_SA(0, 0), a2, voffA);
;             PG8_WAIT_V(8); PG8_WAIT_L(0); PG8_BAR; PG8_MMA(1, 0, At, B0); PG8_MMA(1, 1, At, B1); PG8_BAR; PG8_SCHED;
.LBB0_453:
	s_add_u32 s8, s46, 0xfffc0080
	s_addc_u32 s9, s47, -1
	s_add_i32 s66, 0, 0x10000
	s_cmp_eq_u32 s65, 12
	s_cselect_b32 s49, s54, s9
	s_cselect_b32 s48, s55, s8
	s_cselect_b32 s9, s17, s64
	s_cselect_b32 s8, s56, s57
	s_add_i32 s76, 0, 0x14000
	v_add_u32_e32 v52, s66, v178
	v_add_u32_e32 v168, s76, v178
	s_add_i32 m0, s50, 0xc000
	s_nop 0
	global_load_lds_dwordx4 v152, s[46:47]
	s_add_i32 m0, s50, 0xe000
	s_nop 0
	global_load_lds_dwordx4 v154, s[46:47]
	ds_read_b128 v[40:43], v52
	ds_read_b128 v[44:47], v52 offset:1024
	ds_read_b128 v[48:51], v52 offset:2048
	ds_read_b128 v[52:55], v52 offset:3072
	ds_read_b128 v[156:159], v168
	ds_read_b128 v[160:163], v168 offset:1024
	ds_read_b128 v[164:167], v168 offset:2048
	ds_read_b128 v[168:171], v168 offset:3072
	ds_read_b128 v[172:175], v179
	ds_read_b128 v[180:183], v179 offset:1024
	ds_read_b128 v[184:187], v179 offset:2048
	ds_read_b128 v[188:191], v179 offset:3072
	ds_read_b128 v[212:215], v179 offset:4096
	ds_read_b128 v[216:219], v179 offset:5120
	ds_read_b128 v[220:223], v179 offset:6144
	ds_read_b128 v[224:227], v179 offset:7168
	s_waitcnt vmcnt(8)
	s_waitcnt lgkmcnt(0)
	s_barrier
	s_setprio 1
	s_waitcnt lgkmcnt(0)
	v_mfma_f32_16x16x32_bf16 v[140:143], v[40:43], v[172:175], v[140:143]
	v_mfma_f32_16x16x32_bf16 v[136:139], v[48:51], v[172:175], v[136:139]
	v_mfma_f32_16x16x32_bf16 v[124:127], v[40:43], v[184:187], v[124:127]
	v_mfma_f32_16x16x32_bf16 v[120:123], v[48:51], v[184:187], v[120:123]
	v_mfma_f32_16x16x32_bf16 v[108:111], v[40:43], v[212:215], v[108:111]
	v_mfma_f32_16x16x32_bf16 v[104:107], v[48:51], v[212:215], v[104:107]
	v_mfma_f32_16x16x32_bf16 v[92:95], v[40:43], v[220:223], v[92:95]
	v_mfma_f32_16x16x32_bf16 v[88:91], v[48:51], v[220:223], v[88:91]
	v_mfma_f32_16x16x32_bf16 v[140:143], v[44:47], v[180:183], v[140:143]
	v_mfma_f32_16x16x32_bf16 v[136:139], v[52:55], v[180:183], v[136:139]
	v_mfma_f32_16x16x32_bf16 v[124:127], v[44:47], v[188:191], v[124:127]
	v_mfma_f32_16x16x32_bf16 v[120:123], v[52:55], v[188:191], v[120:123]
	v_mfma_f32_16x16x32_bf16 v[108:111], v[44:47], v[216:219], v[108:111]
	v_mfma_f32_16x16x32_bf16 v[104:107], v[52:55], v[216:219], v[104:107]
	v_mfma_f32_16x16x32_bf16 v[92:95], v[44:47], v[224:227], v[92:95]
	v_mfma_f32_16x16x32_bf16 v[88:91], v[52:55], v[224:227], v[88:91]
	s_setprio 0
	s_setprio 1
	v_mfma_f32_16x16x32_bf16 v[132:135], v[156:159], v[172:175], v[132:135]
	v_mfma_f32_16x16x32_bf16 v[128:131], v[164:167], v[172:175], v[128:131]
	v_mfma_f32_16x16x32_bf16 v[116:119], v[156:159], v[184:187], v[116:119]
	v_mfma_f32_16x16x32_bf16 v[112:115], v[164:167], v[184:187], v[112:115]
	v_mfma_f32_16x16x32_bf16 v[100:103], v[156:159], v[212:215], v[100:103]
	v_mfma_f32_16x16x32_bf16 v[96:99], v[164:167], v[212:215], v[96:99]
	v_mfma_f32_16x16x32_bf16 v[84:87], v[156:159], v[220:223], v[84:87]
	v_mfma_f32_16x16x32_bf16 v[80:83], v[164:167], v[220:223], v[80:83]
	v_mfma_f32_16x16x32_bf16 v[132:135], v[160:163], v[180:183], v[132:135]
	v_mfma_f32_16x16x32_bf16 v[128:131], v[168:171], v[180:183], v[128:131]
	v_mfma_f32_16x16x32_bf16 v[116:119], v[160:163], v[188:191], v[116:119]
	v_mfma_f32_16x16x32_bf16 v[112:115], v[168:171], v[188:191], v[112:115]
	v_mfma_f32_16x16x32_bf16 v[100:103], v[160:163], v[216:219], v[100:103]
	v_mfma_f32_16x16x32_bf16 v[96:99], v[168:171], v[216:219], v[96:99]
	v_mfma_f32_16x16x32_bf16 v[84:87], v[160:163], v[224:227], v[84:87]
	v_mfma_f32_16x16x32_bf16 v[80:83], v[168:171], v[224:227], v[80:83]
	s_setprio 0
	s_barrier
	s_add_i32 s66, s66, s53
	v_lshl_add_u64 v[198:199], s[48:49], 0, v[150:151]
	s_mov_b32 m0, s50
	s_nop 0
	global_load_lds_dwordx4 v150, s[48:49]
	s_mov_b32 m0, s51
	s_nop 0
	global_load_lds_dwordx4 v146, s[48:49]
	s_mov_b32 m0, s66
	ds_read_b128 v[172:175], v179 offset:16384
	ds_read_b128 v[180:183], v179 offset:17408
	ds_read_b128 v[184:187], v179 offset:18432
	ds_read_b128 v[188:191], v179 offset:19456
	ds_read_b128 v[212:215], v179 offset:20480
	ds_read_b128 v[216:219], v179 offset:21504
	ds_read_b128 v[220:223], v179 offset:22528
	ds_read_b128 v[224:227], v179 offset:23552
	global_load_lds_dwordx4 v148, s[8:9]
	s_add_i32 m0, s66, 0x2000
	s_add_u32 s66, s8, 0x40000
	s_addc_u32 s67, s9, 0
	s_add_i32 s76, s76, s53
	global_load_lds_dwordx4 v144, s[8:9]
	s_mov_b32 m0, s76
	v_lshl_add_u64 v[200:201], s[48:49], 0, v[146:147]
	global_load_lds_dwordx4 v148, s[66:67]
	s_add_i32 m0, s76, 0x2000
	s_nop 0
	global_load_lds_dwordx4 v144, s[66:67]
	s_waitcnt vmcnt(8)
	s_waitcnt lgkmcnt(0)
	s_barrier
	s_setprio 1
	s_waitcnt lgkmcnt(0)
	v_mfma_f32_16x16x32_bf16 v[76:79], v[40:43], v[172:175], v[76:79]
	v_mfma_f32_16x16x32_bf16 v[72:75], v[48:51], v[172:175], v[72:75]
	v_mfma_f32_16x16x32_bf16 v[60:63], v[40:43], v[184:187], v[60:63]
	v_mfma_f32_16x16x32_bf16 v[56:59], v[48:51], v[184:187], v[56:59]
	v_mfma_f32_16x16x32_bf16 v[28:31], v[40:43], v[212:215], v[28:31]
	v_mfma_f32_16x16x32_bf16 v[24:27], v[48:51], v[212:215], v[24:27]
	v_mfma_f32_16x16x32_bf16 v[12:15], v[40:43], v[220:223], v[12:15]
	v_mfma_f32_16x16x32_bf16 v[8:11], v[48:51], v[220:223], v[8:11]
	v_mfma_f32_16x16x32_bf16 v[76:79], v[44:47], v[180:183], v[76:79]
	v_mfma_f32_16x16x32_bf16 v[72:75], v[52:55], v[180:183], v[72:75]
	v_mfma_f32_16x16x32_bf16 v[60:63], v[44:47], v[188:191], v[60:63]
	v_mfma_f32_16x16x32_bf16 v[56:59], v[52:55], v[188:191], v[56:59]
	v_mfma_f32_16x16x32_bf16 v[28:31], v[44:47], v[216:219], v[28:31]
	v_mfma_f32_16x16x32_bf16 v[24:27], v[52:55], v[216:219], v[24:27]
	v_mfma_f32_16x16x32_bf16 v[12:15], v[44:47], v[224:227], v[12:15]
	v_mfma_f32_16x16x32_bf16 v[8:11], v[52:55], v[224:227], v[8:11]
	s_setprio 0
	s_setprio 1
	v_mfma_f32_16x16x32_bf16 v[36:39], v[156:159], v[184:187], v[36:39]
	v_mfma_f32_16x16x32_bf16 v[32:35], v[164:167], v[184:187], v[32:35]
	v_mfma_f32_16x16x32_bf16 v[20:23], v[156:159], v[212:215], v[20:23]
	v_mfma_f32_16x16x32_bf16 v[16:19], v[164:167], v[212:215], v[16:19]
	v_mfma_f32_16x16x32_bf16 v[4:7], v[156:159], v[220:223], v[4:7]
	v_mfma_f32_16x16x32_bf16 v[0:3], v[164:167], v[220:223], v[0:3]
	v_mfma_f32_16x16x32_bf16 v[40:43], v[156:159], v[172:175], v[68:71]
	v_mfma_f32_16x16x32_bf16 v[44:47], v[164:167], v[172:175], v[64:67]
	v_mfma_f32_16x16x32_bf16 v[36:39], v[160:163], v[188:191], v[36:39]
	v_mfma_f32_16x16x32_bf16 v[32:35], v[168:171], v[188:191], v[32:35]
	v_mfma_f32_16x16x32_bf16 v[20:23], v[160:163], v[216:219], v[20:23]
	v_mfma_f32_16x16x32_bf16 v[16:19], v[168:171], v[216:219], v[16:19]
	v_mfma_f32_16x16x32_bf16 v[4:7], v[160:163], v[224:227], v[4:7]
	v_mfma_f32_16x16x32_bf16 v[0:3], v[168:171], v[224:227], v[0:3]
	v_mfma_f32_16x16x32_bf16 v[40:43], v[160:163], v[180:183], v[40:43]
	v_mfma_f32_16x16x32_bf16 v[44:47], v[168:171], v[180:183], v[44:47]
	s_setprio 0
	s_barrier
; #define PG8_STAGE(bufoff, gbase, voff) do { _Pragma("unroll") for (int _i = 0; _i < 2; ++_i) \
;         __builtin_amdgcn_global_load_lds((const unsigned*)((const char*)(gbase) + (voff)[_i]), (LAS unsigned*)(lds + (bufoff) + ldsw + _i * 8192), 16, 0, 0); } while (0)
; #define PG8_LDA(dst, b, h) do { _Pragma("unroll") for (int m = 0; m < 4; ++m) _Pragma("unroll") for (int k = 0; k < 2; ++k) dst[m][k] = *(const LAS bf16x8*)(lds + PG8_SA(b, h) + aoff + m * 2048 + k * 1024); } while (0)
; #define PG8_LDB(dst, b, h) do { _Pragma("unroll") for (int n = 0; n < 2; ++n) _Pragma("unroll") for (int k = 0; k < 2; ++k) dst[n][k] = *(const LAS bf16x8*)(lds + PG8_SB(b, h) + boff + n * 2048 + k * 1024); } while (0)
; #define PG8_MMA(ai, bj, At, Bt) do { __builtin_amdgcn_s_setprio(1); _Pragma("unroll") for (int m = 0; m < 4; ++m) _Pragma("unroll") for (int n = 0; n < 2; ++n) _Pragma("unroll") for (int k = 0; k < 2; ++k) \
;         acc[ai][bj][m][n] = __builtin_amdgcn_mfma_f32_16x16x32_bf16(Bt[n][k], At[m][k], acc[ai][bj][m][n], 0, 0, 0); __builtin_amdgcn_s_setprio(0); } while (0)
; #define PG8_WAIT_V(n) asm volatile("s_waitcnt vmcnt(" #n ")" ::: "memory")
; #define PG8_WAIT_L(n) asm volatile("s_waitcnt lgkmcnt(" #n ")" ::: "memory")
; #define PG8_BAR __builtin_amdgcn_s_barrier()
; #define PG8_SCHED __builtin_amdgcn_sched_barrier(0)
; template <class Epi, class Sched, bool ALIGN_EPI>
; __device__ __forceinline__ void gemm_phase(LAS unsigned char* lds, const Gemm g, const Sched& S, const Epi& E) {
;     ...
;             PG8_LDB(B0, 1, 0); PG8_LDB(B1, 1, 1); PG8_SCHED; PG8_LDA(At, 1, 0); PG8_STAGE(PG8_SA(0, 1), a2 + hstepA, voffA);
;             PG8_WAIT_V(8); PG8_WAIT_L(0); PG8_BAR; PG8_MMA(0, 0, At, B0); PG8_MMA(0, 1, At, B1); PG8_BAR; PG8_SCHED;
;             PG8_LDA(At, 1, 1); PG8_STAGE(PG8_SB(1, 0), b3, voffB); PG8_STAGE(PG8_SB(1, 1), b3 + hstepB, voffB); PG8_STAGE(PG8_SA(1, 0), a3, voffA);
;             PG8_WAIT_V(8); PG8_WAIT_L(0); PG8_BAR; PG8_MMA(1, 0, At, B0); PG8_MMA(1, 1, At, B1); PG8_BAR; PG8_SCHED;
;         }
	s_add_i32 s66, 0, 0x18000
	s_add_i32 s67, 0, 0x1c000
	v_add_u32_e32 v68, s66, v178
	v_add_u32_e32 v168, s67, v178
	s_add_u32 s48, s48, 0x40000
	s_addc_u32 s49, s49, 0
	s_mov_b32 m0, s22
	s_nop 0
	global_load_lds_dwordx4 v150, s[48:49]
	s_mov_b32 m0, s23
	s_nop 0
	global_load_lds_dwordx4 v146, s[48:49]
	ds_read_b128 v[48:51], v68
	ds_read_b128 v[52:55], v68 offset:1024
	ds_read_b128 v[64:67], v68 offset:2048
	ds_read_b128 v[68:71], v68 offset:3072
	ds_read_b128 v[156:159], v168
	ds_read_b128 v[160:163], v168 offset:1024
	ds_read_b128 v[164:167], v168 offset:2048
	ds_read_b128 v[168:171], v168 offset:3072
	ds_read_b128 v[172:175], v179 offset:32768
	ds_read_b128 v[180:183], v179 offset:33792
	ds_read_b128 v[184:187], v179 offset:34816
	ds_read_b128 v[188:191], v179 offset:35840
	ds_read_b128 v[212:215], v179 offset:36864
	ds_read_b128 v[216:219], v179 offset:37888
	ds_read_b128 v[220:223], v179 offset:38912
	ds_read_b128 v[224:227], v179 offset:39936
	s_waitcnt vmcnt(8)
	s_waitcnt lgkmcnt(0)
	s_barrier
	s_setprio 1
	s_waitcnt lgkmcnt(0)
	v_mfma_f32_16x16x32_bf16 v[140:143], v[48:51], v[172:175], v[140:143]
	v_mfma_f32_16x16x32_bf16 v[136:139], v[64:67], v[172:175], v[136:139]
	v_mfma_f32_16x16x32_bf16 v[124:127], v[48:51], v[184:187], v[124:127]
	v_mfma_f32_16x16x32_bf16 v[120:123], v[64:67], v[184:187], v[120:123]
	v_mfma_f32_16x16x32_bf16 v[108:111], v[48:51], v[212:215], v[108:111]
	v_mfma_f32_16x16x32_bf16 v[104:107], v[64:67], v[212:215], v[104:107]
	v_mfma_f32_16x16x32_bf16 v[92:95], v[48:51], v[220:223], v[92:95]
	v_mfma_f32_16x16x32_bf16 v[88:91], v[64:67], v[220:223], v[88:91]
	v_mfma_f32_16x16x32_bf16 v[140:143], v[52:55], v[180:183], v[140:143]
	v_mfma_f32_16x16x32_bf16 v[136:139], v[68:71], v[180:183], v[136:139]
	v_mfma_f32_16x16x32_bf16 v[124:127], v[52:55], v[188:191], v[124:127]
	v_mfma_f32_16x16x32_bf16 v[120:123], v[68:71], v[188:191], v[120:123]
	v_mfma_f32_16x16x32_bf16 v[108:111], v[52:55], v[216:219], v[108:111]
	v_mfma_f32_16x16x32_bf16 v[104:107], v[68:71], v[216:219], v[104:107]
	v_mfma_f32_16x16x32_bf16 v[92:95], v[52:55], v[224:227], v[92:95]
	v_mfma_f32_16x16x32_bf16 v[88:91], v[68:71], v[224:227], v[88:91]
	s_setprio 0
	s_setprio 1
	v_mfma_f32_16x16x32_bf16 v[132:135], v[156:159], v[172:175], v[132:135]
	v_mfma_f32_16x16x32_bf16 v[128:131], v[164:167], v[172:175], v[128:131]
	v_mfma_f32_16x16x32_bf16 v[116:119], v[156:159], v[184:187], v[116:119]
	v_mfma_f32_16x16x32_bf16 v[112:115], v[164:167], v[184:187], v[112:115]
	v_mfma_f32_16x16x32_bf16 v[100:103], v[156:159], v[212:215], v[100:103]
	v_mfma_f32_16x16x32_bf16 v[96:99], v[164:167], v[212:215], v[96:99]
	v_mfma_f32_16x16x32_bf16 v[84:87], v[156:159], v[220:223], v[84:87]
	v_mfma_f32_16x16x32_bf16 v[80:83], v[164:167], v[220:223], v[80:83]
	v_mfma_f32_16x16x32_bf16 v[132:135], v[160:163], v[180:183], v[132:135]
	v_mfma_f32_16x16x32_bf16 v[128:131], v[168:171], v[180:183], v[128:131]
	v_mfma_f32_16x16x32_bf16 v[116:119], v[160:163], v[188:191], v[116:119]
	v_mfma_f32_16x16x32_bf16 v[112:115], v[168:171], v[188:191], v[112:115]
	v_mfma_f32_16x16x32_bf16 v[100:103], v[160:163], v[216:219], v[100:103]
	v_mfma_f32_16x16x32_bf16 v[96:99], v[168:171], v[216:219], v[96:99]
	v_mfma_f32_16x16x32_bf16 v[84:87], v[160:163], v[224:227], v[84:87]
	v_mfma_f32_16x16x32_bf16 v[80:83], v[168:171], v[224:227], v[80:83]
	s_setprio 0
	s_barrier
	s_add_i32 s48, s66, s53
	v_lshl_add_u64 v[194:195], v[198:199], 0, s[12:13]
	s_mov_b32 m0, s20
	s_nop 0
	global_load_lds_dwordx4 v[194:195], off
	v_lshl_add_u64 v[194:195], v[200:201], 0, s[12:13]
	s_mov_b32 m0, s21
	s_nop 0
	global_load_lds_dwordx4 v[194:195], off
	s_mov_b32 m0, s48
	ds_read_b128 v[172:175], v179 offset:49152
	ds_read_b128 v[180:183], v179 offset:50176
	ds_read_b128 v[184:187], v179 offset:51200
	ds_read_b128 v[188:191], v179 offset:52224
	ds_read_b128 v[212:215], v179 offset:53248
	ds_read_b128 v[216:219], v179 offset:54272
	ds_read_b128 v[220:223], v179 offset:55296
	ds_read_b128 v[224:227], v179 offset:56320
	s_add_u32 s100, s8, 0x80
	s_addc_u32 s101, s9, 0
	global_load_lds_dwordx4 v148, s[100:101]
	s_add_i32 m0, s48, 0x2000
	s_add_u32 s8, s8, 0x40080
	s_addc_u32 s9, s9, 0
	s_add_i32 s48, s67, s53
	global_load_lds_dwordx4 v144, s[100:101]
	s_mov_b32 m0, s48
	s_nop 0
	global_load_lds_dwordx4 v148, s[8:9]
	s_add_i32 m0, s48, 0x2000
	s_nop 0
	global_load_lds_dwordx4 v144, s[8:9]
	s_waitcnt vmcnt(8)
	s_waitcnt lgkmcnt(0)
	s_barrier
	s_setprio 1
	s_waitcnt lgkmcnt(0)
	v_mfma_f32_16x16x32_bf16 v[76:79], v[48:51], v[172:175], v[76:79]
	v_mfma_f32_16x16x32_bf16 v[72:75], v[64:67], v[172:175], v[72:75]
	v_mfma_f32_16x16x32_bf16 v[60:63], v[48:51], v[184:187], v[60:63]
	v_mfma_f32_16x16x32_bf16 v[56:59], v[64:67], v[184:187], v[56:59]
	v_mfma_f32_16x16x32_bf16 v[28:31], v[48:51], v[212:215], v[28:31]
	v_mfma_f32_16x16x32_bf16 v[24:27], v[64:67], v[212:215], v[24:27]
	v_mfma_f32_16x16x32_bf16 v[12:15], v[48:51], v[220:223], v[12:15]
	v_mfma_f32_16x16x32_bf16 v[8:11], v[64:67], v[220:223], v[8:11]
	v_mfma_f32_16x16x32_bf16 v[76:79], v[52:55], v[180:183], v[76:79]
	v_mfma_f32_16x16x32_bf16 v[72:75], v[68:71], v[180:183], v[72:75]
	v_mfma_f32_16x16x32_bf16 v[60:63], v[52:55], v[188:191], v[60:63]
	v_mfma_f32_16x16x32_bf16 v[56:59], v[68:71], v[188:191], v[56:59]
	v_mfma_f32_16x16x32_bf16 v[28:31], v[52:55], v[216:219], v[28:31]
	v_mfma_f32_16x16x32_bf16 v[24:27], v[68:71], v[216:219], v[24:27]
	v_mfma_f32_16x16x32_bf16 v[12:15], v[52:55], v[224:227], v[12:15]
	v_mfma_f32_16x16x32_bf16 v[8:11], v[68:71], v[224:227], v[8:11]
	s_setprio 0
	s_setprio 1
	v_mfma_f32_16x16x32_bf16 v[40:43], v[156:159], v[172:175], v[40:43]
	v_mfma_f32_16x16x32_bf16 v[68:71], v[160:163], v[180:183], v[40:43]
	v_mfma_f32_16x16x32_bf16 v[40:43], v[164:167], v[172:175], v[44:47]
	v_mfma_f32_16x16x32_bf16 v[36:39], v[156:159], v[184:187], v[36:39]
	v_mfma_f32_16x16x32_bf16 v[32:35], v[164:167], v[184:187], v[32:35]
	v_mfma_f32_16x16x32_bf16 v[20:23], v[156:159], v[212:215], v[20:23]
	v_mfma_f32_16x16x32_bf16 v[16:19], v[164:167], v[212:215], v[16:19]
	v_mfma_f32_16x16x32_bf16 v[4:7], v[156:159], v[220:223], v[4:7]
	v_mfma_f32_16x16x32_bf16 v[0:3], v[164:167], v[220:223], v[0:3]
	v_mfma_f32_16x16x32_bf16 v[64:67], v[168:171], v[180:183], v[40:43]
	v_mfma_f32_16x16x32_bf16 v[36:39], v[160:163], v[188:191], v[36:39]
	v_mfma_f32_16x16x32_bf16 v[32:35], v[168:171], v[188:191], v[32:35]
	v_mfma_f32_16x16x32_bf16 v[20:23], v[160:163], v[216:219], v[20:23]
	v_mfma_f32_16x16x32_bf16 v[16:19], v[168:171], v[216:219], v[16:19]
	v_mfma_f32_16x16x32_bf16 v[4:7], v[160:163], v[224:227], v[4:7]
	v_mfma_f32_16x16x32_bf16 v[0:3], v[168:171], v[224:227], v[0:3]
	s_setprio 0
	s_barrier
	s_add_i32 s65, s65, 2
	s_add_u32 s46, s46, 0x100
	s_addc_u32 s47, s47, 0
	s_add_u32 s57, s57, 0x100
	s_addc_u32 s64, s64, 0
	s_cmp_gt_u32 s65, 13
	s_cbranch_scc0 .LBB0_453
	v_readlane_b32 s8, v255, 58
	v_readlane_b32 s9, v255, 59
	s_and_b64 vcc, exec, s[8:9]
	s_cbranch_vccz .LBB0_456
	s_barrier

; #define PG8_STAGE(bufoff, gbase, voff) do { _Pragma("unroll") for (int _i = 0; _i < 2; ++_i) \
;         __builtin_amdgcn_global_load_lds((const unsigned*)((const char*)(gbase) + (voff)[_i]), (LAS unsigned*)(lds + (bufoff) + ldsw + _i * 8192), 16, 0, 0); } while (0)
; #define PG8_LDA(dst, b, h) do { _Pragma("unroll") for (int m = 0; m < 4; ++m) _Pragma("unroll") for (int k = 0; k < 2; ++k) dst[m][k] = *(const LAS bf16x8*)(lds + PG8_SA(b, h) + aoff + m * 2048 + k * 1024); } while (0)
; #define PG8_LDB(dst, b, h) do { _Pragma("unroll") for (int n = 0; n < 2; ++n) _Pragma("unroll") for (int k = 0; k < 2; ++k) dst[n][k] = *(const LAS bf16x8*)(lds + PG8_SB(b, h) + boff + n * 2048 + k * 1024); } while (0)
; #define PG8_MMA(ai, bj, At, Bt) do { __builtin_amdgcn_s_setprio(1); _Pragma("unroll") for (int m = 0; m < 4; ++m) _Pragma("unroll") for (int n = 0; n < 2; ++n) _Pragma("unroll") for (int k = 0; k < 2; ++k) \
;         acc[ai][bj][m][n] = __builtin_amdgcn_mfma_f32_16x16x32_bf16(Bt[n][k], At[m][k], acc[ai][bj][m][n], 0, 0, 0); __builtin_amdgcn_s_setprio(0); } while (0)
; #define PG8_WAIT_V(n) asm volatile("s_waitcnt vmcnt(" #n ")" ::: "memory")
; #define PG8_WAIT_L(n) asm volatile("s_waitcnt lgkmcnt(" #n ")" ::: "memory")
; #define PG8_BAR __builtin_amdgcn_s_barrier()
; #define PG8_SCHED __builtin_amdgcn_sched_barrier(0)
; template <class Epi, class Sched, bool ALIGN_EPI>
; __device__ __forceinline__ void gemm_phase(LAS unsigned char* lds, const Gemm g, const Sched& S, const Epi& E) {
;     ...
;             const char* a1 = cA + (size_t)(t + 1) * kstep;
;             const char* a2 = last ? nA : cA + (size_t)(t + 2) * kstep; const char* b2 = last ? nB : cB + (size_t)(t + 2) * kstep;
;             const char* a3 = a2 + kstep; const char* b3 = b2 + kstep;
;             PG8_LDB(B0, 0, 0); PG8_LDB(B1, 0, 1); PG8_SCHED; PG8_LDA(At, 0, 0); PG8_STAGE(PG8_SA(1, 1), a1 + hstepA, voffA);
;             PG8_WAIT_V(8); PG8_WAIT_L(0); PG8_BAR; PG8_MMA(0, 0, At, B0); PG8_MMA(0, 1, At, B1); PG8_BAR; PG8_SCHED;
;             PG8_LDA(At, 0, 1); PG8_STAGE(PG8_SB(0, 0), b2, voffB); PG8_STAGE(PG8_SB(0, 1), b2 + hstepB, voffB); PG8_STAGE(PG8_SA(0, 0), a2, voffA);
;             PG8_WAIT_V(8); PG8_WAIT_L(0); PG8_BAR; PG8_MMA(1, 0, At, B0); PG8_MMA(1, 1, At, B1); PG8_BAR; PG8_SCHED;
.LBB0_571:
	s_add_u32 s46, s44, 0xfffc0080
	s_addc_u32 s47, s45, -1
	s_add_i32 vcc_lo, 0, 0x10000
	s_cmp_eq_u32 s92, 12
	s_cselect_b32 s49, s21, s47
	s_cselect_b32 s48, s86, s46
	s_cselect_b32 s47, s17, s91
	s_cselect_b32 s46, s87, s90
	s_add_i32 s4, 0, 0x14000
	v_add_u32_e32 v76, vcc_lo, v162
	v_add_u32_e32 v158, s4, v162
	s_add_i32 m0, s54, 0xc000
	s_nop 0
	global_load_lds_dwordx4 v150, s[44:45]
	s_add_i32 m0, s54, 0xe000
	s_nop 0
	global_load_lds_dwordx4 v152, s[44:45]
	ds_read_b128 v[64:67], v76
	ds_read_b128 v[68:71], v76 offset:1024
	ds_read_b128 v[72:75], v76 offset:2048
	ds_read_b128 v[76:79], v76 offset:3072
	ds_read_b128 v[154:157], v158
	ds_read_b128 v[164:167], v158 offset:1024
	ds_read_b128 v[168:171], v158 offset:2048
	ds_read_b128 v[172:175], v158 offset:3072
	ds_read_b128 v[176:179], v163
	ds_read_b128 v[180:183], v163 offset:1024
	ds_read_b128 v[184:187], v163 offset:2048
	ds_read_b128 v[188:191], v163 offset:3072
	ds_read_b128 v[212:215], v163 offset:4096
	ds_read_b128 v[216:219], v163 offset:5120
	ds_read_b128 v[220:223], v163 offset:6144
	ds_read_b128 v[224:227], v163 offset:7168
	s_waitcnt vmcnt(8)
	s_waitcnt lgkmcnt(0)
	s_barrier
	s_setprio 1
	s_waitcnt lgkmcnt(0)
	v_mfma_f32_16x16x32_bf16 v[140:143], v[64:67], v[176:179], v[140:143]
	v_mfma_f32_16x16x32_bf16 v[136:139], v[72:75], v[176:179], v[136:139]
	v_mfma_f32_16x16x32_bf16 v[124:127], v[64:67], v[184:187], v[124:127]
	v_mfma_f32_16x16x32_bf16 v[120:123], v[72:75], v[184:187], v[120:123]
	v_mfma_f32_16x16x32_bf16 v[108:111], v[64:67], v[212:215], v[108:111]
	v_mfma_f32_16x16x32_bf16 v[104:107], v[72:75], v[212:215], v[104:107]
	v_mfma_f32_16x16x32_bf16 v[92:95], v[64:67], v[220:223], v[92:95]
	v_mfma_f32_16x16x32_bf16 v[88:91], v[72:75], v[220:223], v[88:91]
	v_mfma_f32_16x16x32_bf16 v[140:143], v[68:71], v[180:183], v[140:143]
	v_mfma_f32_16x16x32_bf16 v[136:139], v[76:79], v[180:183], v[136:139]
	v_mfma_f32_16x16x32_bf16 v[124:127], v[68:71], v[188:191], v[124:127]
	v_mfma_f32_16x16x32_bf16 v[120:123], v[76:79], v[188:191], v[120:123]
	v_mfma_f32_16x16x32_bf16 v[108:111], v[68:71], v[216:219], v[108:111]
	v_mfma_f32_16x16x32_bf16 v[104:107], v[76:79], v[216:219], v[104:107]
	v_mfma_f32_16x16x32_bf16 v[92:95], v[68:71], v[224:227], v[92:95]
	v_mfma_f32_16x16x32_bf16 v[88:91], v[76:79], v[224:227], v[88:91]
	s_setprio 0
	s_setprio 1
	v_mfma_f32_16x16x32_bf16 v[132:135], v[154:157], v[176:179], v[132:135]
	v_mfma_f32_16x16x32_bf16 v[128:131], v[168:171], v[176:179], v[128:131]
	v_mfma_f32_16x16x32_bf16 v[116:119], v[154:157], v[184:187], v[116:119]
	v_mfma_f32_16x16x32_bf16 v[112:115], v[168:171], v[184:187], v[112:115]
	v_mfma_f32_16x16x32_bf16 v[100:103], v[154:157], v[212:215], v[100:103]
	v_mfma_f32_16x16x32_bf16 v[96:99], v[168:171], v[212:215], v[96:99]
	v_mfma_f32_16x16x32_bf16 v[84:87], v[154:157], v[220:223], v[84:87]
	v_mfma_f32_16x16x32_bf16 v[80:83], v[168:171], v[220:223], v[80:83]
	v_mfma_f32_16x16x32_bf16 v[132:135], v[164:167], v[180:183], v[132:135]
	v_mfma_f32_16x16x32_bf16 v[128:131], v[172:175], v[180:183], v[128:131]
	v_mfma_f32_16x16x32_bf16 v[116:119], v[164:167], v[188:191], v[116:119]
	v_mfma_f32_16x16x32_bf16 v[112:115], v[172:175], v[188:191], v[112:115]
	v_mfma_f32_16x16x32_bf16 v[100:103], v[164:167], v[216:219], v[100:103]
	v_mfma_f32_16x16x32_bf16 v[96:99], v[172:175], v[216:219], v[96:99]
	v_mfma_f32_16x16x32_bf16 v[84:87], v[164:167], v[224:227], v[84:87]
	v_mfma_f32_16x16x32_bf16 v[80:83], v[172:175], v[224:227], v[80:83]
	s_setprio 0
	s_barrier
	s_add_i32 s5, vcc_lo, s53
	s_mov_b32 m0, s54
	s_nop 0
	global_load_lds_dwordx4 v148, s[48:49]
	s_mov_b32 m0, s55
	s_nop 0
	global_load_lds_dwordx4 v146, s[48:49]
	s_mov_b32 m0, s5
	ds_read_b128 v[176:179], v163 offset:16384
	ds_read_b128 v[180:183], v163 offset:17408
	ds_read_b128 v[184:187], v163 offset:18432
	ds_read_b128 v[188:191], v163 offset:19456
	ds_read_b128 v[212:215], v163 offset:20480
	ds_read_b128 v[216:219], v163 offset:21504
	ds_read_b128 v[220:223], v163 offset:22528
	ds_read_b128 v[224:227], v163 offset:23552
	global_load_lds_dwordx4 v192, s[46:47]
	s_add_i32 m0, s5, 0x2000
	s_add_u32 vcc_lo, s46, 0x40000
	s_addc_u32 vcc_hi, s47, 0
	s_add_i32 s4, s4, s53
	global_load_lds_dwordx4 v144, s[46:47]
	s_mov_b32 m0, s4
	s_nop 0
	global_load_lds_dwordx4 v192, vcc
	s_add_i32 m0, s4, 0x2000
	s_nop 0
	global_load_lds_dwordx4 v144, vcc
	s_waitcnt vmcnt(8)
	s_waitcnt lgkmcnt(0)
	s_barrier
	s_setprio 1
	s_waitcnt lgkmcnt(0)
	v_mfma_f32_16x16x32_bf16 v[60:63], v[64:67], v[176:179], v[60:63]
	v_mfma_f32_16x16x32_bf16 v[56:59], v[72:75], v[176:179], v[56:59]
	v_mfma_f32_16x16x32_bf16 v[44:47], v[64:67], v[184:187], v[44:47]
	v_mfma_f32_16x16x32_bf16 v[40:43], v[72:75], v[184:187], v[40:43]
	v_mfma_f32_16x16x32_bf16 v[28:31], v[64:67], v[212:215], v[28:31]
	v_mfma_f32_16x16x32_bf16 v[24:27], v[72:75], v[212:215], v[24:27]
	v_mfma_f32_16x16x32_bf16 v[12:15], v[64:67], v[220:223], v[12:15]
	v_mfma_f32_16x16x32_bf16 v[8:11], v[72:75], v[220:223], v[8:11]
	v_mfma_f32_16x16x32_bf16 v[60:63], v[68:71], v[180:183], v[60:63]
	v_mfma_f32_16x16x32_bf16 v[56:59], v[76:79], v[180:183], v[56:59]
	v_mfma_f32_16x16x32_bf16 v[44:47], v[68:71], v[188:191], v[44:47]
	v_mfma_f32_16x16x32_bf16 v[40:43], v[76:79], v[188:191], v[40:43]
	v_mfma_f32_16x16x32_bf16 v[28:31], v[68:71], v[216:219], v[28:31]
	v_mfma_f32_16x16x32_bf16 v[24:27], v[76:79], v[216:219], v[24:27]
	v_mfma_f32_16x16x32_bf16 v[12:15], v[68:71], v[224:227], v[12:15]
	v_mfma_f32_16x16x32_bf16 v[8:11], v[76:79], v[224:227], v[8:11]
	s_setprio 0
	s_setprio 1
	v_mfma_f32_16x16x32_bf16 v[52:55], v[154:157], v[176:179], v[52:55]
	v_mfma_f32_16x16x32_bf16 v[48:51], v[168:171], v[176:179], v[48:51]
	v_mfma_f32_16x16x32_bf16 v[36:39], v[154:157], v[184:187], v[36:39]
	v_mfma_f32_16x16x32_bf16 v[32:35], v[168:171], v[184:187], v[32:35]
	v_mfma_f32_16x16x32_bf16 v[20:23], v[154:157], v[212:215], v[20:23]
	v_mfma_f32_16x16x32_bf16 v[16:19], v[168:171], v[212:215], v[16:19]
	v_mfma_f32_16x16x32_bf16 v[4:7], v[154:157], v[220:223], v[4:7]
	v_mfma_f32_16x16x32_bf16 v[0:3], v[168:171], v[220:223], v[0:3]
	v_mfma_f32_16x16x32_bf16 v[52:55], v[164:167], v[180:183], v[52:55]
	v_mfma_f32_16x16x32_bf16 v[48:51], v[172:175], v[180:183], v[48:51]
	v_mfma_f32_16x16x32_bf16 v[36:39], v[164:167], v[188:191], v[36:39]
	v_mfma_f32_16x16x32_bf16 v[32:35], v[172:175], v[188:191], v[32:35]
	v_mfma_f32_16x16x32_bf16 v[20:23], v[164:167], v[216:219], v[20:23]
	v_mfma_f32_16x16x32_bf16 v[16:19], v[172:175], v[216:219], v[16:19]
	v_mfma_f32_16x16x32_bf16 v[4:7], v[164:167], v[224:227], v[4:7]
	v_mfma_f32_16x16x32_bf16 v[0:3], v[172:175], v[224:227], v[0:3]
	s_setprio 0
	s_barrier
; #define PG8_STAGE(bufoff, gbase, voff) do { _Pragma("unroll") for (int _i = 0; _i < 2; ++_i) \
;         __builtin_amdgcn_global_load_lds((const unsigned*)((const char*)(gbase) + (voff)[_i]), (LAS unsigned*)(lds + (bufoff) + ldsw + _i * 8192), 16, 0, 0); } while (0)
; #define PG8_LDA(dst, b, h) do { _Pragma("unroll") for (int m = 0; m < 4; ++m) _Pragma("unroll") for (int k = 0; k < 2; ++k) dst[m][k] = *(const LAS bf16x8*)(lds + PG8_SA(b, h) + aoff + m * 2048 + k * 1024); } while (0)
; #define PG8_LDB(dst, b, h) do { _Pragma("unroll") for (int n = 0; n < 2; ++n) _Pragma("unroll") for (int k = 0; k < 2; ++k) dst[n][k] = *(const LAS bf16x8*)(lds + PG8_SB(b, h) + boff + n * 2048 + k * 1024); } while (0)
; #define PG8_WAIT_V(n) asm volatile("s_waitcnt vmcnt(" #n ")" ::: "memory")
; #define PG8_BAR __builtin_amdgcn_s_barrier()
; template <class Epi, class Sched, bool ALIGN_EPI>
; __device__ __forceinline__ void gemm_phase(LAS unsigned char* lds, const Gemm g, const Sched& S, const Epi& E) {
;     ...
;         for (int t = 0; t < nt; t += 2) {
;             const bool last = (t == nt - 2);
;             const char* a1 = cA + (size_t)(t + 1) * kstep;
;             const char* a2 = last ? nA : cA + (size_t)(t + 2) * kstep; const char* b2 = last ? nB : cB + (size_t)(t + 2) * kstep;
;             const char* a3 = a2 + kstep; const char* b3 = b2 + kstep;
;             PG8_LDB(B0, 0, 0); PG8_LDB(B1, 0, 1); PG8_SCHED; PG8_LDA(At, 0, 0); PG8_STAGE(PG8_SA(1, 1), a1 + hstepA, voffA);
;             PG8_WAIT_V(8); PG8_WAIT_L(0); PG8_BAR; PG8_MMA(0, 0, At, B0); PG8_MMA(0, 1, At, B1); PG8_BAR; PG8_SCHED;
;             PG8_LDA(At, 0, 1); PG8_STAGE(PG8_SB(0, 0), b2, voffB); PG8_STAGE(PG8_SB(0, 1), b2 + hstepB, voffB); PG8_STAGE(PG8_SA(0, 0), a2, voffA);
;             PG8_WAIT_V(8); PG8_WAIT_L(0); PG8_BAR; PG8_MMA(1, 0, At, B0); PG8_MMA(1, 1, At, B1); PG8_BAR; PG8_SCHED;
;             PG8_LDB(B0, 1, 0); PG8_LDB(B1, 1, 1); PG8_SCHED; PG8_LDA(At, 1, 0); PG8_STAGE(PG8_SA(0, 1), a2 + hstepA, voffA);
;             PG8_WAIT_V(8); PG8_WAIT_L(0); PG8_BAR; PG8_MMA(0, 0, At, B0); PG8_MMA(0, 1, At, B1); PG8_BAR; PG8_SCHED;
;             PG8_LDA(At, 1, 1); PG8_STAGE(PG8_SB(1, 0), b3, voffB); PG8_STAGE(PG8_SB(1, 1), b3 + hstepB, voffB); PG8_STAGE(PG8_SA(1, 0), a3, voffA);
;             PG8_WAIT_V(8); PG8_WAIT_L(0); PG8_BAR; PG8_MMA(1, 0, At, B0); PG8_MMA(1, 1, At, B1); PG8_BAR; PG8_SCHED;
	s_add_i32 s4, 0, 0x18000
	s_add_i32 s5, 0, 0x1c000
	v_add_u32_e32 v76, s4, v162
	v_add_u32_e32 v172, s5, v162
	s_add_u32 s48, s48, 0x40000
	s_addc_u32 s49, s49, 0
	s_mov_b32 m0, s56
	s_nop 0
	global_load_lds_dwordx4 v148, s[48:49]
	s_mov_b32 m0, s57
	s_nop 0
	global_load_lds_dwordx4 v146, s[48:49]
	ds_read_b128 v[64:67], v76
	ds_read_b128 v[68:71], v76 offset:1024
	ds_read_b128 v[72:75], v76 offset:2048
	ds_read_b128 v[76:79], v76 offset:3072
	ds_read_b128 v[154:157], v172
	ds_read_b128 v[164:167], v172 offset:1024
	ds_read_b128 v[168:171], v172 offset:2048
	ds_read_b128 v[172:175], v172 offset:3072
	ds_read_b128 v[176:179], v163 offset:32768
	ds_read_b128 v[180:183], v163 offset:33792
	ds_read_b128 v[184:187], v163 offset:34816
	ds_read_b128 v[188:191], v163 offset:35840
	ds_read_b128 v[212:215], v163 offset:36864
	ds_read_b128 v[216:219], v163 offset:37888
	ds_read_b128 v[220:223], v163 offset:38912
	ds_read_b128 v[224:227], v163 offset:39936
	s_waitcnt vmcnt(8)
	s_waitcnt lgkmcnt(0)
	s_barrier
	s_setprio 1
	s_waitcnt lgkmcnt(0)
	v_mfma_f32_16x16x32_bf16 v[140:143], v[64:67], v[176:179], v[140:143]
	v_mfma_f32_16x16x32_bf16 v[136:139], v[72:75], v[176:179], v[136:139]
	v_mfma_f32_16x16x32_bf16 v[124:127], v[64:67], v[184:187], v[124:127]
	v_mfma_f32_16x16x32_bf16 v[120:123], v[72:75], v[184:187], v[120:123]
	v_mfma_f32_16x16x32_bf16 v[108:111], v[64:67], v[212:215], v[108:111]
	v_mfma_f32_16x16x32_bf16 v[104:107], v[72:75], v[212:215], v[104:107]
	v_mfma_f32_16x16x32_bf16 v[92:95], v[64:67], v[220:223], v[92:95]
	v_mfma_f32_16x16x32_bf16 v[88:91], v[72:75], v[220:223], v[88:91]
	v_mfma_f32_16x16x32_bf16 v[140:143], v[68:71], v[180:183], v[140:143]
	v_mfma_f32_16x16x32_bf16 v[136:139], v[76:79], v[180:183], v[136:139]
	v_mfma_f32_16x16x32_bf16 v[124:127], v[68:71], v[188:191], v[124:127]
	v_mfma_f32_16x16x32_bf16 v[120:123], v[76:79], v[188:191], v[120:123]
	v_mfma_f32_16x16x32_bf16 v[108:111], v[68:71], v[216:219], v[108:111]
	v_mfma_f32_16x16x32_bf16 v[104:107], v[76:79], v[216:219], v[104:107]
	v_mfma_f32_16x16x32_bf16 v[92:95], v[68:71], v[224:227], v[92:95]
	v_mfma_f32_16x16x32_bf16 v[88:91], v[76:79], v[224:227], v[88:91]
	s_setprio 0
	s_setprio 1
	v_mfma_f32_16x16x32_bf16 v[132:135], v[154:157], v[176:179], v[132:135]
	v_mfma_f32_16x16x32_bf16 v[128:131], v[168:171], v[176:179], v[128:131]
	v_mfma_f32_16x16x32_bf16 v[116:119], v[154:157], v[184:187], v[116:119]
	v_mfma_f32_16x16x32_bf16 v[112:115], v[168:171], v[184:187], v[112:115]
	v_mfma_f32_16x16x32_bf16 v[100:103], v[154:157], v[212:215], v[100:103]
	v_mfma_f32_16x16x32_bf16 v[96:99], v[168:171], v[212:215], v[96:99]
	v_mfma_f32_16x16x32_bf16 v[84:87], v[154:157], v[220:223], v[84:87]
	v_mfma_f32_16x16x32_bf16 v[80:83], v[168:171], v[220:223], v[80:83]
	v_mfma_f32_16x16x32_bf16 v[132:135], v[164:167], v[180:183], v[132:135]
	v_mfma_f32_16x16x32_bf16 v[128:131], v[172:175], v[180:183], v[128:131]
	v_mfma_f32_16x16x32_bf16 v[116:119], v[164:167], v[188:191], v[116:119]
	v_mfma_f32_16x16x32_bf16 v[112:115], v[172:175], v[188:191], v[112:115]
	v_mfma_f32_16x16x32_bf16 v[100:103], v[164:167], v[216:219], v[100:103]
	v_mfma_f32_16x16x32_bf16 v[96:99], v[172:175], v[216:219], v[96:99]
	v_mfma_f32_16x16x32_bf16 v[84:87], v[164:167], v[224:227], v[84:87]
	v_mfma_f32_16x16x32_bf16 v[80:83], v[172:175], v[224:227], v[80:83]
	s_setprio 0
	s_barrier
	s_add_i32 s4, s4, s53
	s_mov_b32 m0, s65
	s_add_u32 s100, s48, 0xfffc0080
	s_addc_u32 s101, s49, -1
	global_load_lds_dwordx4 v148, s[100:101]
	s_mov_b32 m0, s66
	s_nop 0
	global_load_lds_dwordx4 v146, s[100:101]
	s_mov_b32 m0, s4
	ds_read_b128 v[176:179], v163 offset:49152
	ds_read_b128 v[180:183], v163 offset:50176
	ds_read_b128 v[184:187], v163 offset:51200
	ds_read_b128 v[188:191], v163 offset:52224
	ds_read_b128 v[212:215], v163 offset:53248
	ds_read_b128 v[216:219], v163 offset:54272
	ds_read_b128 v[220:223], v163 offset:55296
	ds_read_b128 v[224:227], v163 offset:56320
	s_add_u32 s100, s46, 0x80
	s_addc_u32 s101, s47, 0
	global_load_lds_dwordx4 v192, s[100:101]
	s_add_i32 m0, s4, 0x2000
	s_add_u32 s46, s46, 0x40080
	s_addc_u32 s47, s47, 0
	s_add_i32 s4, s5, s53
	global_load_lds_dwordx4 v144, s[100:101]
	s_mov_b32 m0, s4
	s_nop 0
	global_load_lds_dwordx4 v192, s[46:47]
	s_add_i32 m0, s4, 0x2000
	s_nop 0
	global_load_lds_dwordx4 v144, s[46:47]
	s_waitcnt vmcnt(8)
	s_waitcnt lgkmcnt(0)
	s_barrier
	s_setprio 1
	s_waitcnt lgkmcnt(0)
	v_mfma_f32_16x16x32_bf16 v[60:63], v[64:67], v[176:179], v[60:63]
	v_mfma_f32_16x16x32_bf16 v[56:59], v[72:75], v[176:179], v[56:59]
	v_mfma_f32_16x16x32_bf16 v[44:47], v[64:67], v[184:187], v[44:47]
	v_mfma_f32_16x16x32_bf16 v[40:43], v[72:75], v[184:187], v[40:43]
	v_mfma_f32_16x16x32_bf16 v[28:31], v[64:67], v[212:215], v[28:31]
	v_mfma_f32_16x16x32_bf16 v[24:27], v[72:75], v[212:215], v[24:27]
	v_mfma_f32_16x16x32_bf16 v[12:15], v[64:67], v[220:223], v[12:15]
	v_mfma_f32_16x16x32_bf16 v[8:11], v[72:75], v[220:223], v[8:11]
	v_mfma_f32_16x16x32_bf16 v[60:63], v[68:71], v[180:183], v[60:63]
	v_mfma_f32_16x16x32_bf16 v[56:59], v[76:79], v[180:183], v[56:59]
	v_mfma_f32_16x16x32_bf16 v[44:47], v[68:71], v[188:191], v[44:47]
	v_mfma_f32_16x16x32_bf16 v[40:43], v[76:79], v[188:191], v[40:43]
	v_mfma_f32_16x16x32_bf16 v[28:31], v[68:71], v[216:219], v[28:31]
	v_mfma_f32_16x16x32_bf16 v[24:27], v[76:79], v[216:219], v[24:27]
	v_mfma_f32_16x16x32_bf16 v[12:15], v[68:71], v[224:227], v[12:15]
	v_mfma_f32_16x16x32_bf16 v[8:11], v[76:79], v[224:227], v[8:11]
	s_setprio 0
	s_setprio 1
	v_mfma_f32_16x16x32_bf16 v[52:55], v[154:157], v[176:179], v[52:55]
	v_mfma_f32_16x16x32_bf16 v[48:51], v[168:171], v[176:179], v[48:51]
	v_mfma_f32_16x16x32_bf16 v[36:39], v[154:157], v[184:187], v[36:39]
	v_mfma_f32_16x16x32_bf16 v[32:35], v[168:171], v[184:187], v[32:35]
	v_mfma_f32_16x16x32_bf16 v[20:23], v[154:157], v[212:215], v[20:23]
	v_mfma_f32_16x16x32_bf16 v[16:19], v[168:171], v[212:215], v[16:19]
	v_mfma_f32_16x16x32_bf16 v[4:7], v[154:157], v[220:223], v[4:7]
	v_mfma_f32_16x16x32_bf16 v[0:3], v[168:171], v[220:223], v[0:3]
	v_mfma_f32_16x16x32_bf16 v[52:55], v[164:167], v[180:183], v[52:55]
	v_mfma_f32_16x16x32_bf16 v[48:51], v[172:175], v[180:183], v[48:51]
	v_mfma_f32_16x16x32_bf16 v[36:39], v[164:167], v[188:191], v[36:39]
	v_mfma_f32_16x16x32_bf16 v[32:35], v[172:175], v[188:191], v[32:35]
	v_mfma_f32_16x16x32_bf16 v[20:23], v[164:167], v[216:219], v[20:23]
	v_mfma_f32_16x16x32_bf16 v[16:19], v[172:175], v[216:219], v[16:19]
	v_mfma_f32_16x16x32_bf16 v[4:7], v[164:167], v[224:227], v[4:7]
	v_mfma_f32_16x16x32_bf16 v[0:3], v[172:175], v[224:227], v[0:3]
	s_setprio 0
	s_barrier
	s_add_i32 s92, s92, 2
	s_add_u32 s44, s44, 0x100
	s_addc_u32 s45, s45, 0
	s_add_u32 s90, s90, 0x100
	s_addc_u32 s91, s91, 0
	s_cmp_gt_u32 s92, 13
	s_cbranch_scc0 .LBB0_571
	s_and_b64 vcc, exec, s[8:9]
	s_cbranch_vccz .LBB0_574
	s_barrier

; __global__ void __launch_bounds__(512, 2) fwd_kernel(Args args) {
	.amdhsa_kernel _Z10fwd_kernel4Args
		.amdhsa_group_segment_fixed_size 0
		.amdhsa_private_segment_fixed_size 0
		.amdhsa_kernarg_size 472
		.amdhsa_user_sgpr_count 2
		.amdhsa_user_sgpr_dispatch_ptr 0
		.amdhsa_user_sgpr_queue_ptr 0
		.amdhsa_user_sgpr_kernarg_segment_ptr 1
		.amdhsa_user_sgpr_dispatch_id 0
		.amdhsa_user_sgpr_kernarg_preload_length 0
		.amdhsa_user_sgpr_kernarg_preload_offset 0
		.amdhsa_user_sgpr_private_segment_size 0
		.amdhsa_uses_dynamic_stack 0
		.amdhsa_enable_private_segment 0
		.amdhsa_system_sgpr_workgroup_id_x 1
		.amdhsa_system_sgpr_workgroup_id_y 0
		.amdhsa_system_sgpr_workgroup_id_z 0
		.amdhsa_system_sgpr_workgroup_info 0
		.amdhsa_system_vgpr_workitem_id 2
		.amdhsa_next_free_vgpr 256
		.amdhsa_next_free_sgpr 102
		.amdhsa_accum_offset 256
		.amdhsa_reserve_vcc 1
		.amdhsa_float_round_mode_32 0
		.amdhsa_float_round_mode_16_64 0
		.amdhsa_float_denorm_mode_32 3
		.amdhsa_float_denorm_mode_16_64 3
		.amdhsa_dx10_clamp 1
		.amdhsa_ieee_mode 1
		.amdhsa_fp16_overflow 0
		.amdhsa_tg_split 0
		.amdhsa_exception_fp_ieee_invalid_op 0
		.amdhsa_exception_fp_denorm_src 0
		.amdhsa_exception_fp_ieee_div_zero 0
		.amdhsa_exception_fp_ieee_overflow 0
		.amdhsa_exception_fp_ieee_underflow 0
		.amdhsa_exception_fp_ieee_inexact 0
		.amdhsa_exception_int_div_zero 0
	.end_amdhsa_kernel

; __global__ void __launch_bounds__(512, 2) fwd_kernel(Args args) {
amdhsa.kernels:
  - .agpr_count:     0
    .args:
      - .offset:         0
        .size:           216
        .value_kind:     by_value
      - .offset:         216
        .size:           4
        .value_kind:     hidden_block_count_x
      - .offset:         220
        .size:           4
        .value_kind:     hidden_block_count_y
      - .offset:         224
        .size:           4
        .value_kind:     hidden_block_count_z
      - .offset:         228
        .size:           2
        .value_kind:     hidden_group_size_x
      - .offset:         230
        .size:           2
        .value_kind:     hidden_group_size_y
      - .offset:         232
        .size:           2
        .value_kind:     hidden_group_size_z
      - .offset:         234
        .size:           2
        .value_kind:     hidden_remainder_x
      - .offset:         236
        .size:           2
        .value_kind:     hidden_remainder_y
      - .offset:         238
        .size:           2
        .value_kind:     hidden_remainder_z
      - .offset:         256
        .size:           8
        .value_kind:     hidden_global_offset_x
      - .offset:         264
        .size:           8
        .value_kind:     hidden_global_offset_y
      - .offset:         272
        .size:           8
        .value_kind:     hidden_global_offset_z
      - .offset:         280
        .size:           2
        .value_kind:     hidden_grid_dims
      - .offset:         304
        .size:           8
        .value_kind:     hidden_multigrid_sync_arg
      - .offset:         336
        .size:           4
        .value_kind:     hidden_dynamic_lds_size
    .group_segment_fixed_size: 0
    .kernarg_segment_align: 8
    .kernarg_segment_size: 472
    .language:       OpenCL C
    .language_version:
      - 2
      - 0
    .max_flat_workgroup_size: 512
    .name:           _Z10fwd_kernel4Args
    .private_segment_fixed_size: 0
    .sgpr_count:     108
    .sgpr_spill_count: 228
    .symbol:         _Z10fwd_kernel4Args.kd
    .uniform_work_group_size: 1
    .uses_dynamic_stack: false
    .vgpr_count:     256
    .vgpr_spill_count: 0
    .wavefront_size: 64
